# EpiPle v2 row reductions by v_permlane16/32_swap instead of ds_bpermute round trips; on v098
# baseline (speedup 1.0000x reference)
; __device__ __forceinline__ u32x4 pack8(const f32x4 v0, const f32x4 v1) { u32x4 w; w.x = cvt_pk_bf16(v0[0], v0[1]); w.y = cvt_pk_bf16(v0[2], v0[3]); w.z = cvt_pk_bf16(v1[0], v1[1]); w.w = cvt_pk_bf16(v1[2], v1[3]); return w; }
; __device__ __forceinline__ float sumsq8(const f32x4 a, const f32x4 b) { return ((a[0] * a[0] + a[1] * a[1]) + (a[2] * a[2] + a[3] * a[3])) + ((b[0] * b[0] + b[1] * b[1]) + (b[2] * b[2] + b[3] * b[3])); }
;     __device__ __forceinline__ void operator()(const f32x4 (&acc)[2][2][4][2], const Unit& u, int wr, int wc, int fr, int fq) const {
;         const int row0 = u.pm * BM + wr * 64 + fr, col0 = u.pn * BM + wc * 32 + 8 * fq;
; #pragma unroll
;         for (int ai = 0; ai < 2; ++ai)
; #pragma unroll
;           for (int mh = 0; mh < 2; ++mh) {
;             u32x4 rv[2][2], pw[2][2]; f32x4 p[2];
; #pragma unroll
;             for (int mm = 0; mm < 2; ++mm) { const int rowl = row0 + ai * HALF + (2 * mh + mm) * 16; p[mm] = *(const f32x4*)(ssq_in + (size_t)rowl * 16 + 4 * fq);
; #pragma unroll
;                 for (int bj = 0; bj < 2; ++bj) { const size_t off = (size_t)rowl * DMODEL + col0 + bj * HALF; rv[mm][bj] = *(const u32x4*)(Rin + off); pw[mm][bj] = *(const u32x4*)(PP + off); } }
; #pragma unroll
;             for (int mm = 0; mm < 2; ++mm) { const int m = 2 * mh + mm; const int row = row0 + ai * HALF + m * 16; float part = 0.f;
;                 float sr = (p[mm][0] + p[mm][1]) + (p[mm][2] + p[mm][3]); sr += __shfl_xor(sr, 16); sr += __shfl_xor(sr, 32); const float r = __builtin_amdgcn_rsqf(sr * (1.0f / DMODEL) + RMS_EPS);
; #pragma unroll
;                 for (int bj = 0; bj < 2; ++bj) { f32x4 r0, r1, p0, p1; unpack8(rv[mm][bj], r0, r1); unpack8(pw[mm][bj], p0, p1);
;                     f32x4 g0 = acc[ai][bj][m][0] * r, g1 = acc[ai][bj][m][1] * r;
; #pragma unroll
;                     for (int e = 0; e < 4; ++e) { g0[e] = __builtin_amdgcn_rcpf(1.f + __builtin_amdgcn_exp2f(-1.4426950408889634f * g0[e])); g1[e] = __builtin_amdgcn_rcpf(1.f + __builtin_amdgcn_exp2f(-1.4426950408889634f * g1[e])); }
;                     const f32x4 h0 = r0 + g0 * p0, h1 = r1 + g1 * p1; part += sumsq8(h0, h1);
;                     *(u32x4*)(XBo + (size_t)row * DMODEL + col0 + bj * HALF) = pack8(h0, h1); }
.LBB0_1136:
	v_readfirstlane_b32 s19, v192
	v_and_b32_e32 v247, 15, v192
	s_bfe_u32 s17, s19, 0x20006
	s_lshr_b32 s19, s19, 8
	s_lshl_b32 s19, s19, 6
	s_lshl_b32 s27, s40, 8
	s_add_i32 s19, s19, s27
	v_add_u32_e32 v247, s19, v247
	v_bfe_u32 v252, v192, 4, 2
	s_lshl_b32 s27, s26, 8
	s_lshl_b32 s28, s17, 5
	s_or_b32 s27, s27, s28
	v_lshl_or_b32 v253, v252, 3, s27
	v_lshlrev_b32_e32 v172, 11, v247
	v_lshl_add_u32 v172, v253, 1, v172
	v_lshlrev_b32_e32 v194, 6, v247
	v_lshl_add_u32 v173, v252, 4, v194
	s_lshl_b32 s28, s26, 4
	s_lshl_b32 s29, s17, 2
	s_add_i32 s28, s28, s29
	v_add_u32_e32 v194, s28, v194
	v_cmp_eq_u32_e32 vcc, 0, v252
	v_xor_b32_e32 v236, 16, v241
	v_xor_b32_e32 v237, 32, v241
	v_lshlrev_b32_e32 v236, 2, v236
	v_lshlrev_b32_e32 v237, 2, v237
	v_mov_b32_e32 v250, v172
	v_mov_b32_e32 v251, v173
	global_load_dwordx4 v[128:131], v251, s[10:11]
	global_load_dwordx4 v[132:135], v250, s[6:7]
	global_load_dwordx4 v[140:143], v250, s[2:3]
	global_load_dwordx4 v[136:139], v250, s[6:7] offset:256
	global_load_dwordx4 v[144:147], v250, s[2:3] offset:256
	v_add_u32_e32 v250, 0x8000, v172
	v_add_u32_e32 v251, 0x400, v173
	global_load_dwordx4 v[160:163], v251, s[10:11]
	global_load_dwordx4 v[164:167], v250, s[6:7]
	global_load_dwordx4 v[176:179], v250, s[2:3]
	global_load_dwordx4 v[168:171], v250, s[6:7] offset:256
	global_load_dwordx4 v[180:183], v250, s[2:3] offset:256
	v_add_u32_e32 v250, 0x10000, v172
	v_add_u32_e32 v251, 0x800, v173
	global_load_dwordx4 v[184:187], v251, s[10:11]
	global_load_dwordx4 v[188:191], v250, s[6:7]
	global_load_dwordx4 v[208:211], v250, s[2:3]
	global_load_dwordx4 v[204:207], v250, s[6:7] offset:256
	global_load_dwordx4 v[212:215], v250, s[2:3] offset:256
	s_waitcnt vmcnt(10)
	v_add_f32_e32 v247, v128, v129
	v_add_f32_e32 v252, v130, v131
	v_add_f32_e32 v247, v247, v252
	v_mov_b32_e32 v252, v247
	s_nop 1
	v_permlane16_swap_b32_e32 v247, v252
	v_add_f32_e32 v247, v247, v252
	v_mov_b32_e32 v252, v247
	s_nop 1
	v_permlane32_swap_b32_e32 v247, v252
	v_add_f32_e32 v247, v247, v252
	v_fmamk_f32 v247, v247, 0x3a800000, v193
	v_rsq_f32_e32 v247, v247
	s_nop 0
	v_mul_f32_e32 v253, 0xbfb8aa3b, v247
	v_mul_f32_e32 v124, v124, v253
	v_mul_f32_e32 v125, v125, v253
	v_mul_f32_e32 v126, v126, v253
	v_mul_f32_e32 v127, v127, v253
	v_exp_f32_e32 v124, v124
	v_exp_f32_e32 v125, v125
	v_exp_f32_e32 v126, v126
	v_exp_f32_e32 v127, v127
	v_add_f32_e32 v124, 1.0, v124
	v_add_f32_e32 v125, 1.0, v125
	v_add_f32_e32 v126, 1.0, v126
	v_add_f32_e32 v127, 1.0, v127
	v_rcp_f32_e32 v124, v124
	v_rcp_f32_e32 v125, v125
	v_rcp_f32_e32 v126, v126
	v_rcp_f32_e32 v127, v127
	v_lshlrev_b32_e32 v224, 16, v132
	v_and_b32_e32 v225, 0xffff0000, v132
	v_lshlrev_b32_e32 v226, 16, v133
	v_and_b32_e32 v227, 0xffff0000, v133
	v_lshlrev_b32_e32 v228, 16, v140
	v_and_b32_e32 v229, 0xffff0000, v140
	v_lshlrev_b32_e32 v230, 16, v141
	v_and_b32_e32 v231, 0xffff0000, v141
	v_fma_f32 v124, v124, v228, v224
	v_fma_f32 v125, v125, v229, v225
	v_fma_f32 v126, v126, v230, v226
	v_fma_f32 v127, v127, v231, v227
	v_mul_f32_e32 v232, v125, v125
	v_mul_f32_e32 v233, v127, v127
	v_fmac_f32_e32 v232, v124, v124
	v_fmac_f32_e32 v233, v126, v126
	v_add_f32_e32 v234, v232, v233
	v_mul_f32_e32 v120, v120, v253
	v_mul_f32_e32 v121, v121, v253
	v_mul_f32_e32 v122, v122, v253
	v_mul_f32_e32 v123, v123, v253
	v_exp_f32_e32 v120, v120
	v_exp_f32_e32 v121, v121
	v_exp_f32_e32 v122, v122
	v_exp_f32_e32 v123, v123
	v_add_f32_e32 v120, 1.0, v120
	v_add_f32_e32 v121, 1.0, v121
	v_add_f32_e32 v122, 1.0, v122
	v_add_f32_e32 v123, 1.0, v123
	v_rcp_f32_e32 v120, v120
	v_rcp_f32_e32 v121, v121
	v_rcp_f32_e32 v122, v122
	v_rcp_f32_e32 v123, v123
	v_lshlrev_b32_e32 v224, 16, v134
	v_and_b32_e32 v225, 0xffff0000, v134
	v_lshlrev_b32_e32 v226, 16, v135
	v_and_b32_e32 v227, 0xffff0000, v135
	v_lshlrev_b32_e32 v228, 16, v142
	v_and_b32_e32 v229, 0xffff0000, v142
	v_lshlrev_b32_e32 v230, 16, v143
	v_and_b32_e32 v231, 0xffff0000, v143
	v_fma_f32 v120, v120, v228, v224
	v_fma_f32 v121, v121, v229, v225
	v_fma_f32 v122, v122, v230, v226
	v_fma_f32 v123, v123, v231, v227
	v_mul_f32_e32 v232, v121, v121
	v_mul_f32_e32 v233, v123, v123
	v_fmac_f32_e32 v232, v120, v120
	v_fmac_f32_e32 v233, v122, v122
	v_add_f32_e32 v235, v232, v233
	v_cvt_pk_bf16_f32 v124, v124, v125
	v_cvt_pk_bf16_f32 v125, v126, v127
	v_cvt_pk_bf16_f32 v126, v120, v121
	v_cvt_pk_bf16_f32 v127, v122, v123
	v_mov_b32_e32 v250, v172
	global_store_dwordx4 v250, v[124:127], s[0:1]
	v_mul_f32_e32 v116, v116, v253
	v_mul_f32_e32 v117, v117, v253
	v_mul_f32_e32 v118, v118, v253
	v_mul_f32_e32 v119, v119, v253
	v_exp_f32_e32 v116, v116
	v_exp_f32_e32 v117, v117
	v_exp_f32_e32 v118, v118
	v_exp_f32_e32 v119, v119
	v_add_f32_e32 v116, 1.0, v116
	v_add_f32_e32 v117, 1.0, v117
	v_add_f32_e32 v118, 1.0, v118
	v_add_f32_e32 v119, 1.0, v119
	v_rcp_f32_e32 v116, v116
	v_rcp_f32_e32 v117, v117
	v_rcp_f32_e32 v118, v118
	v_rcp_f32_e32 v119, v119
	v_lshlrev_b32_e32 v224, 16, v136
	v_and_b32_e32 v225, 0xffff0000, v136
	v_lshlrev_b32_e32 v226, 16, v137
	v_and_b32_e32 v227, 0xffff0000, v137
	v_lshlrev_b32_e32 v228, 16, v144
	v_and_b32_e32 v229, 0xffff0000, v144
	v_lshlrev_b32_e32 v230, 16, v145
	v_and_b32_e32 v231, 0xffff0000, v145
	v_fma_f32 v116, v116, v228, v224
	v_fma_f32 v117, v117, v229, v225
	v_fma_f32 v118, v118, v230, v226
	v_fma_f32 v119, v119, v231, v227
	v_mul_f32_e32 v232, v117, v117
	v_mul_f32_e32 v233, v119, v119
	v_fmac_f32_e32 v232, v116, v116
	v_fmac_f32_e32 v233, v118, v118
	v_add_f32_e32 v248, v232, v233
	v_mul_f32_e32 v112, v112, v253
	v_mul_f32_e32 v113, v113, v253
	v_mul_f32_e32 v114, v114, v253
	v_mul_f32_e32 v115, v115, v253
; __device__ __forceinline__ u32x4 pack8(const f32x4 v0, const f32x4 v1) { u32x4 w; w.x = cvt_pk_bf16(v0[0], v0[1]); w.y = cvt_pk_bf16(v0[2], v0[3]); w.z = cvt_pk_bf16(v1[0], v1[1]); w.w = cvt_pk_bf16(v1[2], v1[3]); return w; }
; __device__ __forceinline__ float sumsq8(const f32x4 a, const f32x4 b) { return ((a[0] * a[0] + a[1] * a[1]) + (a[2] * a[2] + a[3] * a[3])) + ((b[0] * b[0] + b[1] * b[1]) + (b[2] * b[2] + b[3] * b[3])); }
; __device__ __forceinline__ void unpack8(const u32x4 w, f32x4& a, f32x4& b) { a = (f32x4){bf_lo(w.x), bf_hi(w.x), bf_lo(w.y), bf_hi(w.y)}; b = (f32x4){bf_lo(w.z), bf_hi(w.z), bf_lo(w.w), bf_hi(w.w)}; }
;     __device__ __forceinline__ void operator()(const f32x4 (&acc)[2][2][4][2], const Unit& u, int wr, int wc, int fr, int fq) const {
;     ...
;             for (int mm = 0; mm < 2; ++mm) { const int rowl = row0 + ai * HALF + (2 * mh + mm) * 16; p[mm] = *(const f32x4*)(ssq_in + (size_t)rowl * 16 + 4 * fq);
; #pragma unroll
;                 for (int bj = 0; bj < 2; ++bj) { const size_t off = (size_t)rowl * DMODEL + col0 + bj * HALF; rv[mm][bj] = *(const u32x4*)(Rin + off); pw[mm][bj] = *(const u32x4*)(PP + off); } }
; #pragma unroll
;             for (int mm = 0; mm < 2; ++mm) { const int m = 2 * mh + mm; const int row = row0 + ai * HALF + m * 16; float part = 0.f;
;                 float sr = (p[mm][0] + p[mm][1]) + (p[mm][2] + p[mm][3]); sr += __shfl_xor(sr, 16); sr += __shfl_xor(sr, 32); const float r = __builtin_amdgcn_rsqf(sr * (1.0f / DMODEL) + RMS_EPS);
; #pragma unroll
;                 for (int bj = 0; bj < 2; ++bj) { f32x4 r0, r1, p0, p1; unpack8(rv[mm][bj], r0, r1); unpack8(pw[mm][bj], p0, p1);
;                     f32x4 g0 = acc[ai][bj][m][0] * r, g1 = acc[ai][bj][m][1] * r;
; #pragma unroll
;                     for (int e = 0; e < 4; ++e) { g0[e] = __builtin_amdgcn_rcpf(1.f + __builtin_amdgcn_exp2f(-1.4426950408889634f * g0[e])); g1[e] = __builtin_amdgcn_rcpf(1.f + __builtin_amdgcn_exp2f(-1.4426950408889634f * g1[e])); }
;                     const f32x4 h0 = r0 + g0 * p0, h1 = r1 + g1 * p1; part += sumsq8(h0, h1);
;                     *(u32x4*)(XBo + (size_t)row * DMODEL + col0 + bj * HALF) = pack8(h0, h1); }
;                 part += __shfl_xor(part, 16); part += __shfl_xor(part, 32);
;                 if (fq == 0) ssq_out[(size_t)row * 16 + u.pn * 4 + wc] = part; }
	v_exp_f32_e32 v112, v112
	v_exp_f32_e32 v113, v113
	v_exp_f32_e32 v114, v114
	v_exp_f32_e32 v115, v115
	v_add_f32_e32 v112, 1.0, v112
	v_add_f32_e32 v113, 1.0, v113
	v_add_f32_e32 v114, 1.0, v114
	v_add_f32_e32 v115, 1.0, v115
	v_rcp_f32_e32 v112, v112
	v_rcp_f32_e32 v113, v113
	v_rcp_f32_e32 v114, v114
	v_rcp_f32_e32 v115, v115
	v_lshlrev_b32_e32 v224, 16, v138
	v_and_b32_e32 v225, 0xffff0000, v138
	v_lshlrev_b32_e32 v226, 16, v139
	v_and_b32_e32 v227, 0xffff0000, v139
	v_lshlrev_b32_e32 v228, 16, v146
	v_and_b32_e32 v229, 0xffff0000, v146
	v_lshlrev_b32_e32 v230, 16, v147
	v_and_b32_e32 v231, 0xffff0000, v147
	v_fma_f32 v112, v112, v228, v224
	v_fma_f32 v113, v113, v229, v225
	v_fma_f32 v114, v114, v230, v226
	v_fma_f32 v115, v115, v231, v227
	v_mul_f32_e32 v232, v113, v113
	v_mul_f32_e32 v233, v115, v115
	v_fmac_f32_e32 v232, v112, v112
	v_fmac_f32_e32 v233, v114, v114
	v_add_f32_e32 v249, v232, v233
	v_cvt_pk_bf16_f32 v116, v116, v117
	v_cvt_pk_bf16_f32 v117, v118, v119
	v_cvt_pk_bf16_f32 v118, v112, v113
	v_cvt_pk_bf16_f32 v119, v114, v115
	global_store_dwordx4 v250, v[116:119], s[0:1] offset:256
	v_add_f32_e32 v234, v234, v235
	v_add_f32_e32 v248, v248, v249
	v_add_f32_e32 v247, v234, v248
	v_mov_b32_e32 v252, v247
	s_nop 1
	v_permlane16_swap_b32_e32 v247, v252
	v_mov_b32_e32 v251, v194
	v_add_f32_e32 v247, v247, v252
	v_mov_b32_e32 v252, v247
	s_nop 1
	v_permlane32_swap_b32_e32 v247, v252
	v_add_f32_e32 v247, v247, v252
	s_and_saveexec_b64 s[28:29], vcc
	global_store_dword v251, v247, s[12:13]
	s_or_b64 exec, exec, s[28:29]
	v_add_u32_e32 v250, 0x18000, v172
	v_add_u32_e32 v251, 0xc00, v173
	global_load_dwordx4 v[128:131], v251, s[10:11]
	global_load_dwordx4 v[132:135], v250, s[6:7]
	global_load_dwordx4 v[140:143], v250, s[2:3]
	global_load_dwordx4 v[136:139], v250, s[6:7] offset:256
	global_load_dwordx4 v[144:147], v250, s[2:3] offset:256
	v_add_u32_e32 v250, 0x40000, v172
	v_add_u32_e32 v251, 0x2000, v173
	global_load_dwordx4 v[124:127], v251, s[10:11]
	global_load_dwordx4 v[120:123], v250, s[6:7]
	global_load_dwordx4 v[112:115], v250, s[2:3]
	global_load_dwordx4 v[116:119], v250, s[6:7] offset:256
	global_load_dwordx4 v[216:219], v250, s[2:3] offset:256
	s_waitcnt vmcnt(18)
	v_add_f32_e32 v247, v160, v161
	v_add_f32_e32 v252, v162, v163
	v_add_f32_e32 v247, v247, v252
	v_mov_b32_e32 v252, v247
	s_nop 1
	v_permlane16_swap_b32_e32 v247, v252
	v_add_f32_e32 v247, v247, v252
	v_mov_b32_e32 v252, v247
	s_nop 1
	v_permlane32_swap_b32_e32 v247, v252
	v_add_f32_e32 v247, v247, v252
	v_fmamk_f32 v247, v247, 0x3a800000, v193
	v_rsq_f32_e32 v247, v247
	s_nop 0
	v_mul_f32_e32 v253, 0xbfb8aa3b, v247
	v_mul_f32_e32 v108, v108, v253
	v_mul_f32_e32 v109, v109, v253
	v_mul_f32_e32 v110, v110, v253
	v_mul_f32_e32 v111, v111, v253
	v_exp_f32_e32 v108, v108
	v_exp_f32_e32 v109, v109
	v_exp_f32_e32 v110, v110
	v_exp_f32_e32 v111, v111
	v_add_f32_e32 v108, 1.0, v108
	v_add_f32_e32 v109, 1.0, v109
	v_add_f32_e32 v110, 1.0, v110
	v_add_f32_e32 v111, 1.0, v111
	v_rcp_f32_e32 v108, v108
	v_rcp_f32_e32 v109, v109
	v_rcp_f32_e32 v110, v110
	v_rcp_f32_e32 v111, v111
	v_lshlrev_b32_e32 v224, 16, v164
	v_and_b32_e32 v225, 0xffff0000, v164
	v_lshlrev_b32_e32 v226, 16, v165
	v_and_b32_e32 v227, 0xffff0000, v165
	v_lshlrev_b32_e32 v228, 16, v176
	v_and_b32_e32 v229, 0xffff0000, v176
	v_lshlrev_b32_e32 v230, 16, v177
	v_and_b32_e32 v231, 0xffff0000, v177
	v_fma_f32 v108, v108, v228, v224
	v_fma_f32 v109, v109, v229, v225
	v_fma_f32 v110, v110, v230, v226
	v_fma_f32 v111, v111, v231, v227
	v_mul_f32_e32 v232, v109, v109
	v_mul_f32_e32 v233, v111, v111
	v_fmac_f32_e32 v232, v108, v108
	v_fmac_f32_e32 v233, v110, v110
	v_add_f32_e32 v234, v232, v233
	v_mul_f32_e32 v104, v104, v253
	v_mul_f32_e32 v105, v105, v253
	v_mul_f32_e32 v106, v106, v253
	v_mul_f32_e32 v107, v107, v253
	v_exp_f32_e32 v104, v104
	v_exp_f32_e32 v105, v105
	v_exp_f32_e32 v106, v106
	v_exp_f32_e32 v107, v107
	v_add_f32_e32 v104, 1.0, v104
	v_add_f32_e32 v105, 1.0, v105
	v_add_f32_e32 v106, 1.0, v106
	v_add_f32_e32 v107, 1.0, v107
	v_rcp_f32_e32 v104, v104
	v_rcp_f32_e32 v105, v105
	v_rcp_f32_e32 v106, v106
	v_rcp_f32_e32 v107, v107
	v_lshlrev_b32_e32 v224, 16, v166
	v_and_b32_e32 v225, 0xffff0000, v166
	v_lshlrev_b32_e32 v226, 16, v167
	v_and_b32_e32 v227, 0xffff0000, v167
	v_lshlrev_b32_e32 v228, 16, v178
	v_and_b32_e32 v229, 0xffff0000, v178
	v_lshlrev_b32_e32 v230, 16, v179
	v_and_b32_e32 v231, 0xffff0000, v179
	v_fma_f32 v104, v104, v228, v224
	v_fma_f32 v105, v105, v229, v225
	v_fma_f32 v106, v106, v230, v226
	v_fma_f32 v107, v107, v231, v227
	v_mul_f32_e32 v232, v105, v105
	v_mul_f32_e32 v233, v107, v107
	v_fmac_f32_e32 v232, v104, v104
	v_fmac_f32_e32 v233, v106, v106
	v_add_f32_e32 v235, v232, v233
	v_cvt_pk_bf16_f32 v108, v108, v109
	v_cvt_pk_bf16_f32 v109, v110, v111
	v_cvt_pk_bf16_f32 v110, v104, v105
	v_cvt_pk_bf16_f32 v111, v106, v107
	v_add_u32_e32 v250, 0x8000, v172
	global_store_dwordx4 v250, v[108:111], s[0:1]
	v_mul_f32_e32 v100, v100, v253
	v_mul_f32_e32 v101, v101, v253
	v_mul_f32_e32 v102, v102, v253
	v_mul_f32_e32 v103, v103, v253
	v_exp_f32_e32 v100, v100
	v_exp_f32_e32 v101, v101
	v_exp_f32_e32 v102, v102
	v_exp_f32_e32 v103, v103
	v_add_f32_e32 v100, 1.0, v100
	v_add_f32_e32 v101, 1.0, v101
	v_add_f32_e32 v102, 1.0, v102
	v_add_f32_e32 v103, 1.0, v103
	v_rcp_f32_e32 v100, v100
	v_rcp_f32_e32 v101, v101
	v_rcp_f32_e32 v102, v102
	v_rcp_f32_e32 v103, v103
	v_lshlrev_b32_e32 v224, 16, v168
	v_and_b32_e32 v225, 0xffff0000, v168
	v_lshlrev_b32_e32 v226, 16, v169
	v_and_b32_e32 v227, 0xffff0000, v169
	v_lshlrev_b32_e32 v228, 16, v180
	v_and_b32_e32 v229, 0xffff0000, v180
; __device__ __forceinline__ u32x4 pack8(const f32x4 v0, const f32x4 v1) { u32x4 w; w.x = cvt_pk_bf16(v0[0], v0[1]); w.y = cvt_pk_bf16(v0[2], v0[3]); w.z = cvt_pk_bf16(v1[0], v1[1]); w.w = cvt_pk_bf16(v1[2], v1[3]); return w; }
; __device__ __forceinline__ float sumsq8(const f32x4 a, const f32x4 b) { return ((a[0] * a[0] + a[1] * a[1]) + (a[2] * a[2] + a[3] * a[3])) + ((b[0] * b[0] + b[1] * b[1]) + (b[2] * b[2] + b[3] * b[3])); }
; __device__ __forceinline__ void unpack8(const u32x4 w, f32x4& a, f32x4& b) { a = (f32x4){bf_lo(w.x), bf_hi(w.x), bf_lo(w.y), bf_hi(w.y)}; b = (f32x4){bf_lo(w.z), bf_hi(w.z), bf_lo(w.w), bf_hi(w.w)}; }
;     __device__ __forceinline__ void operator()(const f32x4 (&acc)[2][2][4][2], const Unit& u, int wr, int wc, int fr, int fq) const {
;     ...
;             for (int mm = 0; mm < 2; ++mm) { const int rowl = row0 + ai * HALF + (2 * mh + mm) * 16; p[mm] = *(const f32x4*)(ssq_in + (size_t)rowl * 16 + 4 * fq);
; #pragma unroll
;                 for (int bj = 0; bj < 2; ++bj) { const size_t off = (size_t)rowl * DMODEL + col0 + bj * HALF; rv[mm][bj] = *(const u32x4*)(Rin + off); pw[mm][bj] = *(const u32x4*)(PP + off); } }
; #pragma unroll
;             for (int mm = 0; mm < 2; ++mm) { const int m = 2 * mh + mm; const int row = row0 + ai * HALF + m * 16; float part = 0.f;
;                 float sr = (p[mm][0] + p[mm][1]) + (p[mm][2] + p[mm][3]); sr += __shfl_xor(sr, 16); sr += __shfl_xor(sr, 32); const float r = __builtin_amdgcn_rsqf(sr * (1.0f / DMODEL) + RMS_EPS);
; #pragma unroll
;                 for (int bj = 0; bj < 2; ++bj) { f32x4 r0, r1, p0, p1; unpack8(rv[mm][bj], r0, r1); unpack8(pw[mm][bj], p0, p1);
;                     f32x4 g0 = acc[ai][bj][m][0] * r, g1 = acc[ai][bj][m][1] * r;
; #pragma unroll
;                     for (int e = 0; e < 4; ++e) { g0[e] = __builtin_amdgcn_rcpf(1.f + __builtin_amdgcn_exp2f(-1.4426950408889634f * g0[e])); g1[e] = __builtin_amdgcn_rcpf(1.f + __builtin_amdgcn_exp2f(-1.4426950408889634f * g1[e])); }
;                     const f32x4 h0 = r0 + g0 * p0, h1 = r1 + g1 * p1; part += sumsq8(h0, h1);
;                     *(u32x4*)(XBo + (size_t)row * DMODEL + col0 + bj * HALF) = pack8(h0, h1); }
;                 part += __shfl_xor(part, 16); part += __shfl_xor(part, 32);
;                 if (fq == 0) ssq_out[(size_t)row * 16 + u.pn * 4 + wc] = part; }
	v_lshlrev_b32_e32 v230, 16, v181
	v_and_b32_e32 v231, 0xffff0000, v181
	v_fma_f32 v100, v100, v228, v224
	v_fma_f32 v101, v101, v229, v225
	v_fma_f32 v102, v102, v230, v226
	v_fma_f32 v103, v103, v231, v227
	v_mul_f32_e32 v232, v101, v101
	v_mul_f32_e32 v233, v103, v103
	v_fmac_f32_e32 v232, v100, v100
	v_fmac_f32_e32 v233, v102, v102
	v_add_f32_e32 v248, v232, v233
	v_mul_f32_e32 v96, v96, v253
	v_mul_f32_e32 v97, v97, v253
	v_mul_f32_e32 v98, v98, v253
	v_mul_f32_e32 v99, v99, v253
	v_exp_f32_e32 v96, v96
	v_exp_f32_e32 v97, v97
	v_exp_f32_e32 v98, v98
	v_exp_f32_e32 v99, v99
	v_add_f32_e32 v96, 1.0, v96
	v_add_f32_e32 v97, 1.0, v97
	v_add_f32_e32 v98, 1.0, v98
	v_add_f32_e32 v99, 1.0, v99
	v_rcp_f32_e32 v96, v96
	v_rcp_f32_e32 v97, v97
	v_rcp_f32_e32 v98, v98
	v_rcp_f32_e32 v99, v99
	v_lshlrev_b32_e32 v224, 16, v170
	v_and_b32_e32 v225, 0xffff0000, v170
	v_lshlrev_b32_e32 v226, 16, v171
	v_and_b32_e32 v227, 0xffff0000, v171
	v_lshlrev_b32_e32 v228, 16, v182
	v_and_b32_e32 v229, 0xffff0000, v182
	v_lshlrev_b32_e32 v230, 16, v183
	v_and_b32_e32 v231, 0xffff0000, v183
	v_fma_f32 v96, v96, v228, v224
	v_fma_f32 v97, v97, v229, v225
	v_fma_f32 v98, v98, v230, v226
	v_fma_f32 v99, v99, v231, v227
	v_mul_f32_e32 v232, v97, v97
	v_mul_f32_e32 v233, v99, v99
	v_fmac_f32_e32 v232, v96, v96
	v_fmac_f32_e32 v233, v98, v98
	v_add_f32_e32 v249, v232, v233
	v_cvt_pk_bf16_f32 v100, v100, v101
	v_cvt_pk_bf16_f32 v101, v102, v103
	v_cvt_pk_bf16_f32 v102, v96, v97
	v_cvt_pk_bf16_f32 v103, v98, v99
	global_store_dwordx4 v250, v[100:103], s[0:1] offset:256
	v_add_f32_e32 v234, v234, v235
	v_add_f32_e32 v248, v248, v249
	v_add_f32_e32 v247, v234, v248
	v_mov_b32_e32 v252, v247
	s_nop 1
	v_permlane16_swap_b32_e32 v247, v252
	v_add_u32_e32 v251, 0x400, v194
	v_add_f32_e32 v247, v247, v252
	v_mov_b32_e32 v252, v247
	s_nop 1
	v_permlane32_swap_b32_e32 v247, v252
	v_add_f32_e32 v247, v247, v252
	s_and_saveexec_b64 s[28:29], vcc
	global_store_dword v251, v247, s[12:13]
	s_or_b64 exec, exec, s[28:29]
	v_add_u32_e32 v250, 0x48000, v172
	v_add_u32_e32 v251, 0x2400, v173
	global_load_dwordx4 v[160:163], v251, s[10:11]
	global_load_dwordx4 v[164:167], v250, s[6:7]
	global_load_dwordx4 v[176:179], v250, s[2:3]
	global_load_dwordx4 v[168:171], v250, s[6:7] offset:256
	global_load_dwordx4 v[180:183], v250, s[2:3] offset:256
	v_add_u32_e32 v250, 0x50000, v172
	v_add_u32_e32 v251, 0x2800, v173
	global_load_dwordx4 v[108:111], v251, s[10:11]
	global_load_dwordx4 v[104:107], v250, s[6:7]
	global_load_dwordx4 v[96:99], v250, s[2:3]
	global_load_dwordx4 v[100:103], v250, s[6:7] offset:256
	global_load_dwordx4 v[220:223], v250, s[2:3] offset:256
	s_waitcnt vmcnt(26)
	v_add_f32_e32 v247, v184, v185
	v_add_f32_e32 v252, v186, v187
	v_add_f32_e32 v247, v247, v252
	v_mov_b32_e32 v252, v247
	s_nop 1
	v_permlane16_swap_b32_e32 v247, v252
	v_add_f32_e32 v247, v247, v252
	v_mov_b32_e32 v252, v247
	s_nop 1
	v_permlane32_swap_b32_e32 v247, v252
	v_add_f32_e32 v247, v247, v252
	v_fmamk_f32 v247, v247, 0x3a800000, v193
	v_rsq_f32_e32 v247, v247
	s_nop 0
	v_mul_f32_e32 v253, 0xbfb8aa3b, v247
	v_mul_f32_e32 v92, v92, v253
	v_mul_f32_e32 v93, v93, v253
	v_mul_f32_e32 v94, v94, v253
	v_mul_f32_e32 v95, v95, v253
	v_exp_f32_e32 v92, v92
	v_exp_f32_e32 v93, v93
	v_exp_f32_e32 v94, v94
	v_exp_f32_e32 v95, v95
	v_add_f32_e32 v92, 1.0, v92
	v_add_f32_e32 v93, 1.0, v93
	v_add_f32_e32 v94, 1.0, v94
	v_add_f32_e32 v95, 1.0, v95
	v_rcp_f32_e32 v92, v92
	v_rcp_f32_e32 v93, v93
	v_rcp_f32_e32 v94, v94
	v_rcp_f32_e32 v95, v95
	v_lshlrev_b32_e32 v224, 16, v188
	v_and_b32_e32 v225, 0xffff0000, v188
	v_lshlrev_b32_e32 v226, 16, v189
	v_and_b32_e32 v227, 0xffff0000, v189
	v_lshlrev_b32_e32 v228, 16, v208
	v_and_b32_e32 v229, 0xffff0000, v208
	v_lshlrev_b32_e32 v230, 16, v209
	v_and_b32_e32 v231, 0xffff0000, v209
	v_fma_f32 v92, v92, v228, v224
	v_fma_f32 v93, v93, v229, v225
	v_fma_f32 v94, v94, v230, v226
	v_fma_f32 v95, v95, v231, v227
	v_mul_f32_e32 v232, v93, v93
	v_mul_f32_e32 v233, v95, v95
	v_fmac_f32_e32 v232, v92, v92
	v_fmac_f32_e32 v233, v94, v94
	v_add_f32_e32 v234, v232, v233
	v_mul_f32_e32 v88, v88, v253
	v_mul_f32_e32 v89, v89, v253
	v_mul_f32_e32 v90, v90, v253
	v_mul_f32_e32 v91, v91, v253
	v_exp_f32_e32 v88, v88
	v_exp_f32_e32 v89, v89
	v_exp_f32_e32 v90, v90
	v_exp_f32_e32 v91, v91
	v_add_f32_e32 v88, 1.0, v88
	v_add_f32_e32 v89, 1.0, v89
	v_add_f32_e32 v90, 1.0, v90
	v_add_f32_e32 v91, 1.0, v91
	v_rcp_f32_e32 v88, v88
	v_rcp_f32_e32 v89, v89
	v_rcp_f32_e32 v90, v90
	v_rcp_f32_e32 v91, v91
	v_lshlrev_b32_e32 v224, 16, v190
	v_and_b32_e32 v225, 0xffff0000, v190
	v_lshlrev_b32_e32 v226, 16, v191
	v_and_b32_e32 v227, 0xffff0000, v191
	v_lshlrev_b32_e32 v228, 16, v210
	v_and_b32_e32 v229, 0xffff0000, v210
	v_lshlrev_b32_e32 v230, 16, v211
	v_and_b32_e32 v231, 0xffff0000, v211
	v_fma_f32 v88, v88, v228, v224
	v_fma_f32 v89, v89, v229, v225
	v_fma_f32 v90, v90, v230, v226
	v_fma_f32 v91, v91, v231, v227
	v_mul_f32_e32 v232, v89, v89
	v_mul_f32_e32 v233, v91, v91
	v_fmac_f32_e32 v232, v88, v88
	v_fmac_f32_e32 v233, v90, v90
	v_add_f32_e32 v235, v232, v233
	v_cvt_pk_bf16_f32 v92, v92, v93
	v_cvt_pk_bf16_f32 v93, v94, v95
	v_cvt_pk_bf16_f32 v94, v88, v89
	v_cvt_pk_bf16_f32 v95, v90, v91
	v_add_u32_e32 v250, 0x10000, v172
	global_store_dwordx4 v250, v[92:95], s[0:1]
	v_mul_f32_e32 v84, v84, v253
	v_mul_f32_e32 v85, v85, v253
	v_mul_f32_e32 v86, v86, v253
	v_mul_f32_e32 v87, v87, v253
	v_exp_f32_e32 v84, v84
	v_exp_f32_e32 v85, v85
	v_exp_f32_e32 v86, v86
	v_exp_f32_e32 v87, v87
	v_add_f32_e32 v84, 1.0, v84
	v_add_f32_e32 v85, 1.0, v85
	v_add_f32_e32 v86, 1.0, v86
	v_add_f32_e32 v87, 1.0, v87
; __device__ __forceinline__ u32x4 pack8(const f32x4 v0, const f32x4 v1) { u32x4 w; w.x = cvt_pk_bf16(v0[0], v0[1]); w.y = cvt_pk_bf16(v0[2], v0[3]); w.z = cvt_pk_bf16(v1[0], v1[1]); w.w = cvt_pk_bf16(v1[2], v1[3]); return w; }
; __device__ __forceinline__ float sumsq8(const f32x4 a, const f32x4 b) { return ((a[0] * a[0] + a[1] * a[1]) + (a[2] * a[2] + a[3] * a[3])) + ((b[0] * b[0] + b[1] * b[1]) + (b[2] * b[2] + b[3] * b[3])); }
; __device__ __forceinline__ void unpack8(const u32x4 w, f32x4& a, f32x4& b) { a = (f32x4){bf_lo(w.x), bf_hi(w.x), bf_lo(w.y), bf_hi(w.y)}; b = (f32x4){bf_lo(w.z), bf_hi(w.z), bf_lo(w.w), bf_hi(w.w)}; }
;     __device__ __forceinline__ void operator()(const f32x4 (&acc)[2][2][4][2], const Unit& u, int wr, int wc, int fr, int fq) const {
;     ...
;             for (int mm = 0; mm < 2; ++mm) { const int rowl = row0 + ai * HALF + (2 * mh + mm) * 16; p[mm] = *(const f32x4*)(ssq_in + (size_t)rowl * 16 + 4 * fq);
; #pragma unroll
;                 for (int bj = 0; bj < 2; ++bj) { const size_t off = (size_t)rowl * DMODEL + col0 + bj * HALF; rv[mm][bj] = *(const u32x4*)(Rin + off); pw[mm][bj] = *(const u32x4*)(PP + off); } }
; #pragma unroll
;             for (int mm = 0; mm < 2; ++mm) { const int m = 2 * mh + mm; const int row = row0 + ai * HALF + m * 16; float part = 0.f;
;                 float sr = (p[mm][0] + p[mm][1]) + (p[mm][2] + p[mm][3]); sr += __shfl_xor(sr, 16); sr += __shfl_xor(sr, 32); const float r = __builtin_amdgcn_rsqf(sr * (1.0f / DMODEL) + RMS_EPS);
; #pragma unroll
;                 for (int bj = 0; bj < 2; ++bj) { f32x4 r0, r1, p0, p1; unpack8(rv[mm][bj], r0, r1); unpack8(pw[mm][bj], p0, p1);
;                     f32x4 g0 = acc[ai][bj][m][0] * r, g1 = acc[ai][bj][m][1] * r;
; #pragma unroll
;                     for (int e = 0; e < 4; ++e) { g0[e] = __builtin_amdgcn_rcpf(1.f + __builtin_amdgcn_exp2f(-1.4426950408889634f * g0[e])); g1[e] = __builtin_amdgcn_rcpf(1.f + __builtin_amdgcn_exp2f(-1.4426950408889634f * g1[e])); }
;                     const f32x4 h0 = r0 + g0 * p0, h1 = r1 + g1 * p1; part += sumsq8(h0, h1);
;                     *(u32x4*)(XBo + (size_t)row * DMODEL + col0 + bj * HALF) = pack8(h0, h1); }
;                 part += __shfl_xor(part, 16); part += __shfl_xor(part, 32);
;                 if (fq == 0) ssq_out[(size_t)row * 16 + u.pn * 4 + wc] = part; }
	v_rcp_f32_e32 v84, v84
	v_rcp_f32_e32 v85, v85
	v_rcp_f32_e32 v86, v86
	v_rcp_f32_e32 v87, v87
	v_lshlrev_b32_e32 v224, 16, v204
	v_and_b32_e32 v225, 0xffff0000, v204
	v_lshlrev_b32_e32 v226, 16, v205
	v_and_b32_e32 v227, 0xffff0000, v205
	v_lshlrev_b32_e32 v228, 16, v212
	v_and_b32_e32 v229, 0xffff0000, v212
	v_lshlrev_b32_e32 v230, 16, v213
	v_and_b32_e32 v231, 0xffff0000, v213
	v_fma_f32 v84, v84, v228, v224
	v_fma_f32 v85, v85, v229, v225
	v_fma_f32 v86, v86, v230, v226
	v_fma_f32 v87, v87, v231, v227
	v_mul_f32_e32 v232, v85, v85
	v_mul_f32_e32 v233, v87, v87
	v_fmac_f32_e32 v232, v84, v84
	v_fmac_f32_e32 v233, v86, v86
	v_add_f32_e32 v248, v232, v233
	v_mul_f32_e32 v80, v80, v253
	v_mul_f32_e32 v81, v81, v253
	v_mul_f32_e32 v82, v82, v253
	v_mul_f32_e32 v83, v83, v253
	v_exp_f32_e32 v80, v80
	v_exp_f32_e32 v81, v81
	v_exp_f32_e32 v82, v82
	v_exp_f32_e32 v83, v83
	v_add_f32_e32 v80, 1.0, v80
	v_add_f32_e32 v81, 1.0, v81
	v_add_f32_e32 v82, 1.0, v82
	v_add_f32_e32 v83, 1.0, v83
	v_rcp_f32_e32 v80, v80
	v_rcp_f32_e32 v81, v81
	v_rcp_f32_e32 v82, v82
	v_rcp_f32_e32 v83, v83
	v_lshlrev_b32_e32 v224, 16, v206
	v_and_b32_e32 v225, 0xffff0000, v206
	v_lshlrev_b32_e32 v226, 16, v207
	v_and_b32_e32 v227, 0xffff0000, v207
	v_lshlrev_b32_e32 v228, 16, v214
	v_and_b32_e32 v229, 0xffff0000, v214
	v_lshlrev_b32_e32 v230, 16, v215
	v_and_b32_e32 v231, 0xffff0000, v215
	v_fma_f32 v80, v80, v228, v224
	v_fma_f32 v81, v81, v229, v225
	v_fma_f32 v82, v82, v230, v226
	v_fma_f32 v83, v83, v231, v227
	v_mul_f32_e32 v232, v81, v81
	v_mul_f32_e32 v233, v83, v83
	v_fmac_f32_e32 v232, v80, v80
	v_fmac_f32_e32 v233, v82, v82
	v_add_f32_e32 v249, v232, v233
	v_cvt_pk_bf16_f32 v84, v84, v85
	v_cvt_pk_bf16_f32 v85, v86, v87
	v_cvt_pk_bf16_f32 v86, v80, v81
	v_cvt_pk_bf16_f32 v87, v82, v83
	global_store_dwordx4 v250, v[84:87], s[0:1] offset:256
	v_add_f32_e32 v234, v234, v235
	v_add_f32_e32 v248, v248, v249
	v_add_f32_e32 v247, v234, v248
	v_mov_b32_e32 v252, v247
	s_nop 1
	v_permlane16_swap_b32_e32 v247, v252
	v_add_u32_e32 v251, 0x800, v194
	v_add_f32_e32 v247, v247, v252
	v_mov_b32_e32 v252, v247
	s_nop 1
	v_permlane32_swap_b32_e32 v247, v252
	v_add_f32_e32 v247, v247, v252
	s_and_saveexec_b64 s[28:29], vcc
	global_store_dword v251, v247, s[12:13]
	s_or_b64 exec, exec, s[28:29]
	v_add_u32_e32 v250, 0x58000, v172
	v_add_u32_e32 v251, 0x2c00, v173
	global_load_dwordx4 v[184:187], v251, s[10:11]
	global_load_dwordx4 v[188:191], v250, s[6:7]
	global_load_dwordx4 v[208:211], v250, s[2:3]
	global_load_dwordx4 v[204:207], v250, s[6:7] offset:256
	global_load_dwordx4 v[212:215], v250, s[2:3] offset:256
	s_waitcnt vmcnt(26)
	v_add_f32_e32 v247, v128, v129
	v_add_f32_e32 v252, v130, v131
	v_add_f32_e32 v247, v247, v252
	v_mov_b32_e32 v252, v247
	s_nop 1
	v_permlane16_swap_b32_e32 v247, v252
	v_add_f32_e32 v247, v247, v252
	v_mov_b32_e32 v252, v247
	s_nop 1
	v_permlane32_swap_b32_e32 v247, v252
	v_add_f32_e32 v247, v247, v252
	v_fmamk_f32 v247, v247, 0x3a800000, v193
	v_rsq_f32_e32 v247, v247
	s_nop 0
	v_mul_f32_e32 v253, 0xbfb8aa3b, v247
	v_mul_f32_e32 v76, v76, v253
	v_mul_f32_e32 v77, v77, v253
	v_mul_f32_e32 v78, v78, v253
	v_mul_f32_e32 v79, v79, v253
	v_exp_f32_e32 v76, v76
	v_exp_f32_e32 v77, v77
	v_exp_f32_e32 v78, v78
	v_exp_f32_e32 v79, v79
	v_add_f32_e32 v76, 1.0, v76
	v_add_f32_e32 v77, 1.0, v77
	v_add_f32_e32 v78, 1.0, v78
	v_add_f32_e32 v79, 1.0, v79
	v_rcp_f32_e32 v76, v76
	v_rcp_f32_e32 v77, v77
	v_rcp_f32_e32 v78, v78
	v_rcp_f32_e32 v79, v79
	v_lshlrev_b32_e32 v224, 16, v132
	v_and_b32_e32 v225, 0xffff0000, v132
	v_lshlrev_b32_e32 v226, 16, v133
	v_and_b32_e32 v227, 0xffff0000, v133
	v_lshlrev_b32_e32 v228, 16, v140
	v_and_b32_e32 v229, 0xffff0000, v140
	v_lshlrev_b32_e32 v230, 16, v141
	v_and_b32_e32 v231, 0xffff0000, v141
	v_fma_f32 v76, v76, v228, v224
	v_fma_f32 v77, v77, v229, v225
	v_fma_f32 v78, v78, v230, v226
	v_fma_f32 v79, v79, v231, v227
	v_mul_f32_e32 v232, v77, v77
	v_mul_f32_e32 v233, v79, v79
	v_fmac_f32_e32 v232, v76, v76
	v_fmac_f32_e32 v233, v78, v78
	v_add_f32_e32 v234, v232, v233
	v_mul_f32_e32 v72, v72, v253
	v_mul_f32_e32 v73, v73, v253
	v_mul_f32_e32 v74, v74, v253
	v_mul_f32_e32 v75, v75, v253
	v_exp_f32_e32 v72, v72
	v_exp_f32_e32 v73, v73
	v_exp_f32_e32 v74, v74
	v_exp_f32_e32 v75, v75
	v_add_f32_e32 v72, 1.0, v72
	v_add_f32_e32 v73, 1.0, v73
	v_add_f32_e32 v74, 1.0, v74
	v_add_f32_e32 v75, 1.0, v75
	v_rcp_f32_e32 v72, v72
	v_rcp_f32_e32 v73, v73
	v_rcp_f32_e32 v74, v74
	v_rcp_f32_e32 v75, v75
	v_lshlrev_b32_e32 v224, 16, v134
	v_and_b32_e32 v225, 0xffff0000, v134
	v_lshlrev_b32_e32 v226, 16, v135
	v_and_b32_e32 v227, 0xffff0000, v135
	v_lshlrev_b32_e32 v228, 16, v142
	v_and_b32_e32 v229, 0xffff0000, v142
	v_lshlrev_b32_e32 v230, 16, v143
	v_and_b32_e32 v231, 0xffff0000, v143
	v_fma_f32 v72, v72, v228, v224
	v_fma_f32 v73, v73, v229, v225
	v_fma_f32 v74, v74, v230, v226
	v_fma_f32 v75, v75, v231, v227
	v_mul_f32_e32 v232, v73, v73
	v_mul_f32_e32 v233, v75, v75
	v_fmac_f32_e32 v232, v72, v72
	v_fmac_f32_e32 v233, v74, v74
	v_add_f32_e32 v235, v232, v233
	v_cvt_pk_bf16_f32 v76, v76, v77
	v_cvt_pk_bf16_f32 v77, v78, v79
	v_cvt_pk_bf16_f32 v78, v72, v73
	v_cvt_pk_bf16_f32 v79, v74, v75
	v_add_u32_e32 v250, 0x18000, v172
	global_store_dwordx4 v250, v[76:79], s[0:1]
	v_mul_f32_e32 v68, v68, v253
	v_mul_f32_e32 v69, v69, v253
	v_mul_f32_e32 v70, v70, v253
	v_mul_f32_e32 v71, v71, v253
	v_exp_f32_e32 v68, v68
	v_exp_f32_e32 v69, v69
	v_exp_f32_e32 v70, v70
	v_exp_f32_e32 v71, v71
	v_add_f32_e32 v68, 1.0, v68
	v_add_f32_e32 v69, 1.0, v69
	v_add_f32_e32 v70, 1.0, v70
	v_add_f32_e32 v71, 1.0, v71
	v_rcp_f32_e32 v68, v68
	v_rcp_f32_e32 v69, v69
; __device__ __forceinline__ u32x4 pack8(const f32x4 v0, const f32x4 v1) { u32x4 w; w.x = cvt_pk_bf16(v0[0], v0[1]); w.y = cvt_pk_bf16(v0[2], v0[3]); w.z = cvt_pk_bf16(v1[0], v1[1]); w.w = cvt_pk_bf16(v1[2], v1[3]); return w; }
; __device__ __forceinline__ float sumsq8(const f32x4 a, const f32x4 b) { return ((a[0] * a[0] + a[1] * a[1]) + (a[2] * a[2] + a[3] * a[3])) + ((b[0] * b[0] + b[1] * b[1]) + (b[2] * b[2] + b[3] * b[3])); }
; __device__ __forceinline__ void unpack8(const u32x4 w, f32x4& a, f32x4& b) { a = (f32x4){bf_lo(w.x), bf_hi(w.x), bf_lo(w.y), bf_hi(w.y)}; b = (f32x4){bf_lo(w.z), bf_hi(w.z), bf_lo(w.w), bf_hi(w.w)}; }
;     __device__ __forceinline__ void operator()(const f32x4 (&acc)[2][2][4][2], const Unit& u, int wr, int wc, int fr, int fq) const {
;     ...
;             for (int mm = 0; mm < 2; ++mm) { const int rowl = row0 + ai * HALF + (2 * mh + mm) * 16; p[mm] = *(const f32x4*)(ssq_in + (size_t)rowl * 16 + 4 * fq);
; #pragma unroll
;                 for (int bj = 0; bj < 2; ++bj) { const size_t off = (size_t)rowl * DMODEL + col0 + bj * HALF; rv[mm][bj] = *(const u32x4*)(Rin + off); pw[mm][bj] = *(const u32x4*)(PP + off); } }
; #pragma unroll
;             for (int mm = 0; mm < 2; ++mm) { const int m = 2 * mh + mm; const int row = row0 + ai * HALF + m * 16; float part = 0.f;
;                 float sr = (p[mm][0] + p[mm][1]) + (p[mm][2] + p[mm][3]); sr += __shfl_xor(sr, 16); sr += __shfl_xor(sr, 32); const float r = __builtin_amdgcn_rsqf(sr * (1.0f / DMODEL) + RMS_EPS);
; #pragma unroll
;                 for (int bj = 0; bj < 2; ++bj) { f32x4 r0, r1, p0, p1; unpack8(rv[mm][bj], r0, r1); unpack8(pw[mm][bj], p0, p1);
;                     f32x4 g0 = acc[ai][bj][m][0] * r, g1 = acc[ai][bj][m][1] * r;
; #pragma unroll
;                     for (int e = 0; e < 4; ++e) { g0[e] = __builtin_amdgcn_rcpf(1.f + __builtin_amdgcn_exp2f(-1.4426950408889634f * g0[e])); g1[e] = __builtin_amdgcn_rcpf(1.f + __builtin_amdgcn_exp2f(-1.4426950408889634f * g1[e])); }
;                     const f32x4 h0 = r0 + g0 * p0, h1 = r1 + g1 * p1; part += sumsq8(h0, h1);
;                     *(u32x4*)(XBo + (size_t)row * DMODEL + col0 + bj * HALF) = pack8(h0, h1); }
;                 part += __shfl_xor(part, 16); part += __shfl_xor(part, 32);
;                 if (fq == 0) ssq_out[(size_t)row * 16 + u.pn * 4 + wc] = part; }
	v_rcp_f32_e32 v70, v70
	v_rcp_f32_e32 v71, v71
	v_lshlrev_b32_e32 v224, 16, v136
	v_and_b32_e32 v225, 0xffff0000, v136
	v_lshlrev_b32_e32 v226, 16, v137
	v_and_b32_e32 v227, 0xffff0000, v137
	v_lshlrev_b32_e32 v228, 16, v144
	v_and_b32_e32 v229, 0xffff0000, v144
	v_lshlrev_b32_e32 v230, 16, v145
	v_and_b32_e32 v231, 0xffff0000, v145
	v_fma_f32 v68, v68, v228, v224
	v_fma_f32 v69, v69, v229, v225
	v_fma_f32 v70, v70, v230, v226
	v_fma_f32 v71, v71, v231, v227
	v_mul_f32_e32 v232, v69, v69
	v_mul_f32_e32 v233, v71, v71
	v_fmac_f32_e32 v232, v68, v68
	v_fmac_f32_e32 v233, v70, v70
	v_add_f32_e32 v248, v232, v233
	v_mul_f32_e32 v64, v64, v253
	v_mul_f32_e32 v65, v65, v253
	v_mul_f32_e32 v66, v66, v253
	v_mul_f32_e32 v67, v67, v253
	v_exp_f32_e32 v64, v64
	v_exp_f32_e32 v65, v65
	v_exp_f32_e32 v66, v66
	v_exp_f32_e32 v67, v67
	v_add_f32_e32 v64, 1.0, v64
	v_add_f32_e32 v65, 1.0, v65
	v_add_f32_e32 v66, 1.0, v66
	v_add_f32_e32 v67, 1.0, v67
	v_rcp_f32_e32 v64, v64
	v_rcp_f32_e32 v65, v65
	v_rcp_f32_e32 v66, v66
	v_rcp_f32_e32 v67, v67
	v_lshlrev_b32_e32 v224, 16, v138
	v_and_b32_e32 v225, 0xffff0000, v138
	v_lshlrev_b32_e32 v226, 16, v139
	v_and_b32_e32 v227, 0xffff0000, v139
	v_lshlrev_b32_e32 v228, 16, v146
	v_and_b32_e32 v229, 0xffff0000, v146
	v_lshlrev_b32_e32 v230, 16, v147
	v_and_b32_e32 v231, 0xffff0000, v147
	v_fma_f32 v64, v64, v228, v224
	v_fma_f32 v65, v65, v229, v225
	v_fma_f32 v66, v66, v230, v226
	v_fma_f32 v67, v67, v231, v227
	v_mul_f32_e32 v232, v65, v65
	v_mul_f32_e32 v233, v67, v67
	v_fmac_f32_e32 v232, v64, v64
	v_fmac_f32_e32 v233, v66, v66
	v_add_f32_e32 v249, v232, v233
	v_cvt_pk_bf16_f32 v68, v68, v69
	v_cvt_pk_bf16_f32 v69, v70, v71
	v_cvt_pk_bf16_f32 v70, v64, v65
	v_cvt_pk_bf16_f32 v71, v66, v67
	global_store_dwordx4 v250, v[68:71], s[0:1] offset:256
	v_add_f32_e32 v234, v234, v235
	v_add_f32_e32 v248, v248, v249
	v_add_f32_e32 v247, v234, v248
	v_mov_b32_e32 v252, v247
	s_nop 1
	v_permlane16_swap_b32_e32 v247, v252
	v_add_u32_e32 v251, 0xc00, v194
	v_add_f32_e32 v247, v247, v252
	v_mov_b32_e32 v252, v247
	s_nop 1
	v_permlane32_swap_b32_e32 v247, v252
	v_add_f32_e32 v247, v247, v252
	s_and_saveexec_b64 s[28:29], vcc
	global_store_dword v251, v247, s[12:13]
	s_or_b64 exec, exec, s[28:29]
	s_waitcnt vmcnt(24)
	v_add_f32_e32 v247, v124, v125
	v_add_f32_e32 v252, v126, v127
	v_add_f32_e32 v247, v247, v252
	v_mov_b32_e32 v252, v247
	s_nop 1
	v_permlane16_swap_b32_e32 v247, v252
	v_add_f32_e32 v247, v247, v252
	v_mov_b32_e32 v252, v247
	s_nop 1
	v_permlane32_swap_b32_e32 v247, v252
	v_add_f32_e32 v247, v247, v252
	v_fmamk_f32 v247, v247, 0x3a800000, v193
	v_rsq_f32_e32 v247, v247
	s_nop 0
	v_mul_f32_e32 v253, 0xbfb8aa3b, v247
	v_mul_f32_e32 v60, v60, v253
	v_mul_f32_e32 v61, v61, v253
	v_mul_f32_e32 v62, v62, v253
	v_mul_f32_e32 v63, v63, v253
	v_exp_f32_e32 v60, v60
	v_exp_f32_e32 v61, v61
	v_exp_f32_e32 v62, v62
	v_exp_f32_e32 v63, v63
	v_add_f32_e32 v60, 1.0, v60
	v_add_f32_e32 v61, 1.0, v61
	v_add_f32_e32 v62, 1.0, v62
	v_add_f32_e32 v63, 1.0, v63
	v_rcp_f32_e32 v60, v60
	v_rcp_f32_e32 v61, v61
	v_rcp_f32_e32 v62, v62
	v_rcp_f32_e32 v63, v63
	v_lshlrev_b32_e32 v224, 16, v120
	v_and_b32_e32 v225, 0xffff0000, v120
	v_lshlrev_b32_e32 v226, 16, v121
	v_and_b32_e32 v227, 0xffff0000, v121
	v_lshlrev_b32_e32 v228, 16, v112
	v_and_b32_e32 v229, 0xffff0000, v112
	v_lshlrev_b32_e32 v230, 16, v113
	v_and_b32_e32 v231, 0xffff0000, v113
	v_fma_f32 v60, v60, v228, v224
	v_fma_f32 v61, v61, v229, v225
	v_fma_f32 v62, v62, v230, v226
	v_fma_f32 v63, v63, v231, v227
	v_mul_f32_e32 v232, v61, v61
	v_mul_f32_e32 v233, v63, v63
	v_fmac_f32_e32 v232, v60, v60
	v_fmac_f32_e32 v233, v62, v62
	v_add_f32_e32 v234, v232, v233
	v_mul_f32_e32 v56, v56, v253
	v_mul_f32_e32 v57, v57, v253
	v_mul_f32_e32 v58, v58, v253
	v_mul_f32_e32 v59, v59, v253
	v_exp_f32_e32 v56, v56
	v_exp_f32_e32 v57, v57
	v_exp_f32_e32 v58, v58
	v_exp_f32_e32 v59, v59
	v_add_f32_e32 v56, 1.0, v56
	v_add_f32_e32 v57, 1.0, v57
	v_add_f32_e32 v58, 1.0, v58
	v_add_f32_e32 v59, 1.0, v59
	v_rcp_f32_e32 v56, v56
	v_rcp_f32_e32 v57, v57
	v_rcp_f32_e32 v58, v58
	v_rcp_f32_e32 v59, v59
	v_lshlrev_b32_e32 v224, 16, v122
	v_and_b32_e32 v225, 0xffff0000, v122
	v_lshlrev_b32_e32 v226, 16, v123
	v_and_b32_e32 v227, 0xffff0000, v123
	v_lshlrev_b32_e32 v228, 16, v114
	v_and_b32_e32 v229, 0xffff0000, v114
	v_lshlrev_b32_e32 v230, 16, v115
	v_and_b32_e32 v231, 0xffff0000, v115
	v_fma_f32 v56, v56, v228, v224
	v_fma_f32 v57, v57, v229, v225
	v_fma_f32 v58, v58, v230, v226
	v_fma_f32 v59, v59, v231, v227
	v_mul_f32_e32 v232, v57, v57
	v_mul_f32_e32 v233, v59, v59
	v_fmac_f32_e32 v232, v56, v56
	v_fmac_f32_e32 v233, v58, v58
	v_add_f32_e32 v235, v232, v233
	v_cvt_pk_bf16_f32 v60, v60, v61
	v_cvt_pk_bf16_f32 v61, v62, v63
	v_cvt_pk_bf16_f32 v62, v56, v57
	v_cvt_pk_bf16_f32 v63, v58, v59
	v_add_u32_e32 v250, 0x40000, v172
	global_store_dwordx4 v250, v[60:63], s[0:1]
	v_mul_f32_e32 v52, v52, v253
	v_mul_f32_e32 v53, v53, v253
	v_mul_f32_e32 v54, v54, v253
	v_mul_f32_e32 v55, v55, v253
	v_exp_f32_e32 v52, v52
	v_exp_f32_e32 v53, v53
	v_exp_f32_e32 v54, v54
	v_exp_f32_e32 v55, v55
	v_add_f32_e32 v52, 1.0, v52
	v_add_f32_e32 v53, 1.0, v53
	v_add_f32_e32 v54, 1.0, v54
	v_add_f32_e32 v55, 1.0, v55
	v_rcp_f32_e32 v52, v52
	v_rcp_f32_e32 v53, v53
	v_rcp_f32_e32 v54, v54
	v_rcp_f32_e32 v55, v55
	v_lshlrev_b32_e32 v224, 16, v116
	v_and_b32_e32 v225, 0xffff0000, v116
	v_lshlrev_b32_e32 v226, 16, v117
	v_and_b32_e32 v227, 0xffff0000, v117
	v_lshlrev_b32_e32 v228, 16, v216
	v_and_b32_e32 v229, 0xffff0000, v216
	v_lshlrev_b32_e32 v230, 16, v217
	v_and_b32_e32 v231, 0xffff0000, v217
	v_fma_f32 v52, v52, v228, v224
; __device__ __forceinline__ u32x4 pack8(const f32x4 v0, const f32x4 v1) { u32x4 w; w.x = cvt_pk_bf16(v0[0], v0[1]); w.y = cvt_pk_bf16(v0[2], v0[3]); w.z = cvt_pk_bf16(v1[0], v1[1]); w.w = cvt_pk_bf16(v1[2], v1[3]); return w; }
; __device__ __forceinline__ float sumsq8(const f32x4 a, const f32x4 b) { return ((a[0] * a[0] + a[1] * a[1]) + (a[2] * a[2] + a[3] * a[3])) + ((b[0] * b[0] + b[1] * b[1]) + (b[2] * b[2] + b[3] * b[3])); }
; __device__ __forceinline__ void unpack8(const u32x4 w, f32x4& a, f32x4& b) { a = (f32x4){bf_lo(w.x), bf_hi(w.x), bf_lo(w.y), bf_hi(w.y)}; b = (f32x4){bf_lo(w.z), bf_hi(w.z), bf_lo(w.w), bf_hi(w.w)}; }
;     __device__ __forceinline__ void operator()(const f32x4 (&acc)[2][2][4][2], const Unit& u, int wr, int wc, int fr, int fq) const {
;     ...
;             for (int mm = 0; mm < 2; ++mm) { const int rowl = row0 + ai * HALF + (2 * mh + mm) * 16; p[mm] = *(const f32x4*)(ssq_in + (size_t)rowl * 16 + 4 * fq);
; #pragma unroll
;                 for (int bj = 0; bj < 2; ++bj) { const size_t off = (size_t)rowl * DMODEL + col0 + bj * HALF; rv[mm][bj] = *(const u32x4*)(Rin + off); pw[mm][bj] = *(const u32x4*)(PP + off); } }
; #pragma unroll
;             for (int mm = 0; mm < 2; ++mm) { const int m = 2 * mh + mm; const int row = row0 + ai * HALF + m * 16; float part = 0.f;
;                 float sr = (p[mm][0] + p[mm][1]) + (p[mm][2] + p[mm][3]); sr += __shfl_xor(sr, 16); sr += __shfl_xor(sr, 32); const float r = __builtin_amdgcn_rsqf(sr * (1.0f / DMODEL) + RMS_EPS);
; #pragma unroll
;                 for (int bj = 0; bj < 2; ++bj) { f32x4 r0, r1, p0, p1; unpack8(rv[mm][bj], r0, r1); unpack8(pw[mm][bj], p0, p1);
;                     f32x4 g0 = acc[ai][bj][m][0] * r, g1 = acc[ai][bj][m][1] * r;
; #pragma unroll
;                     for (int e = 0; e < 4; ++e) { g0[e] = __builtin_amdgcn_rcpf(1.f + __builtin_amdgcn_exp2f(-1.4426950408889634f * g0[e])); g1[e] = __builtin_amdgcn_rcpf(1.f + __builtin_amdgcn_exp2f(-1.4426950408889634f * g1[e])); }
;                     const f32x4 h0 = r0 + g0 * p0, h1 = r1 + g1 * p1; part += sumsq8(h0, h1);
;                     *(u32x4*)(XBo + (size_t)row * DMODEL + col0 + bj * HALF) = pack8(h0, h1); }
;                 part += __shfl_xor(part, 16); part += __shfl_xor(part, 32);
;                 if (fq == 0) ssq_out[(size_t)row * 16 + u.pn * 4 + wc] = part; }
	v_fma_f32 v53, v53, v229, v225
	v_fma_f32 v54, v54, v230, v226
	v_fma_f32 v55, v55, v231, v227
	v_mul_f32_e32 v232, v53, v53
	v_mul_f32_e32 v233, v55, v55
	v_fmac_f32_e32 v232, v52, v52
	v_fmac_f32_e32 v233, v54, v54
	v_add_f32_e32 v248, v232, v233
	v_mul_f32_e32 v48, v48, v253
	v_mul_f32_e32 v49, v49, v253
	v_mul_f32_e32 v50, v50, v253
	v_mul_f32_e32 v51, v51, v253
	v_exp_f32_e32 v48, v48
	v_exp_f32_e32 v49, v49
	v_exp_f32_e32 v50, v50
	v_exp_f32_e32 v51, v51
	v_add_f32_e32 v48, 1.0, v48
	v_add_f32_e32 v49, 1.0, v49
	v_add_f32_e32 v50, 1.0, v50
	v_add_f32_e32 v51, 1.0, v51
	v_rcp_f32_e32 v48, v48
	v_rcp_f32_e32 v49, v49
	v_rcp_f32_e32 v50, v50
	v_rcp_f32_e32 v51, v51
	v_lshlrev_b32_e32 v224, 16, v118
	v_and_b32_e32 v225, 0xffff0000, v118
	v_lshlrev_b32_e32 v226, 16, v119
	v_and_b32_e32 v227, 0xffff0000, v119
	v_lshlrev_b32_e32 v228, 16, v218
	v_and_b32_e32 v229, 0xffff0000, v218
	v_lshlrev_b32_e32 v230, 16, v219
	v_and_b32_e32 v231, 0xffff0000, v219
	v_fma_f32 v48, v48, v228, v224
	v_fma_f32 v49, v49, v229, v225
	v_fma_f32 v50, v50, v230, v226
	v_fma_f32 v51, v51, v231, v227
	v_mul_f32_e32 v232, v49, v49
	v_mul_f32_e32 v233, v51, v51
	v_fmac_f32_e32 v232, v48, v48
	v_fmac_f32_e32 v233, v50, v50
	v_add_f32_e32 v249, v232, v233
	v_cvt_pk_bf16_f32 v52, v52, v53
	v_cvt_pk_bf16_f32 v53, v54, v55
	v_cvt_pk_bf16_f32 v54, v48, v49
	v_cvt_pk_bf16_f32 v55, v50, v51
	global_store_dwordx4 v250, v[52:55], s[0:1] offset:256
	v_add_f32_e32 v234, v234, v235
	v_add_f32_e32 v248, v248, v249
	v_add_f32_e32 v247, v234, v248
	v_mov_b32_e32 v252, v247
	s_nop 1
	v_permlane16_swap_b32_e32 v247, v252
	v_add_u32_e32 v251, 0x2000, v194
	v_add_f32_e32 v247, v247, v252
	v_mov_b32_e32 v252, v247
	s_nop 1
	v_permlane32_swap_b32_e32 v247, v252
	v_add_f32_e32 v247, v247, v252
	s_and_saveexec_b64 s[28:29], vcc
	global_store_dword v251, v247, s[12:13]
	s_or_b64 exec, exec, s[28:29]
	s_waitcnt vmcnt(19)
	v_add_f32_e32 v247, v160, v161
	v_add_f32_e32 v252, v162, v163
	v_add_f32_e32 v247, v247, v252
	v_mov_b32_e32 v252, v247
	s_nop 1
	v_permlane16_swap_b32_e32 v247, v252
	v_add_f32_e32 v247, v247, v252
	v_mov_b32_e32 v252, v247
	s_nop 1
	v_permlane32_swap_b32_e32 v247, v252
	v_add_f32_e32 v247, v247, v252
	v_fmamk_f32 v247, v247, 0x3a800000, v193
	v_rsq_f32_e32 v247, v247
	s_nop 0
	v_mul_f32_e32 v253, 0xbfb8aa3b, v247
	v_mul_f32_e32 v44, v44, v253
	v_mul_f32_e32 v45, v45, v253
	v_mul_f32_e32 v46, v46, v253
	v_mul_f32_e32 v47, v47, v253
	v_exp_f32_e32 v44, v44
	v_exp_f32_e32 v45, v45
	v_exp_f32_e32 v46, v46
	v_exp_f32_e32 v47, v47
	v_add_f32_e32 v44, 1.0, v44
	v_add_f32_e32 v45, 1.0, v45
	v_add_f32_e32 v46, 1.0, v46
	v_add_f32_e32 v47, 1.0, v47
	v_rcp_f32_e32 v44, v44
	v_rcp_f32_e32 v45, v45
	v_rcp_f32_e32 v46, v46
	v_rcp_f32_e32 v47, v47
	v_lshlrev_b32_e32 v224, 16, v164
	v_and_b32_e32 v225, 0xffff0000, v164
	v_lshlrev_b32_e32 v226, 16, v165
	v_and_b32_e32 v227, 0xffff0000, v165
	v_lshlrev_b32_e32 v228, 16, v176
	v_and_b32_e32 v229, 0xffff0000, v176
	v_lshlrev_b32_e32 v230, 16, v177
	v_and_b32_e32 v231, 0xffff0000, v177
	v_fma_f32 v44, v44, v228, v224
	v_fma_f32 v45, v45, v229, v225
	v_fma_f32 v46, v46, v230, v226
	v_fma_f32 v47, v47, v231, v227
	v_mul_f32_e32 v232, v45, v45
	v_mul_f32_e32 v233, v47, v47
	v_fmac_f32_e32 v232, v44, v44
	v_fmac_f32_e32 v233, v46, v46
	v_add_f32_e32 v234, v232, v233
	v_mul_f32_e32 v40, v40, v253
	v_mul_f32_e32 v41, v41, v253
	v_mul_f32_e32 v42, v42, v253
	v_mul_f32_e32 v43, v43, v253
	v_exp_f32_e32 v40, v40
	v_exp_f32_e32 v41, v41
	v_exp_f32_e32 v42, v42
	v_exp_f32_e32 v43, v43
	v_add_f32_e32 v40, 1.0, v40
	v_add_f32_e32 v41, 1.0, v41
	v_add_f32_e32 v42, 1.0, v42
	v_add_f32_e32 v43, 1.0, v43
	v_rcp_f32_e32 v40, v40
	v_rcp_f32_e32 v41, v41
	v_rcp_f32_e32 v42, v42
	v_rcp_f32_e32 v43, v43
	v_lshlrev_b32_e32 v224, 16, v166
	v_and_b32_e32 v225, 0xffff0000, v166
	v_lshlrev_b32_e32 v226, 16, v167
	v_and_b32_e32 v227, 0xffff0000, v167
	v_lshlrev_b32_e32 v228, 16, v178
	v_and_b32_e32 v229, 0xffff0000, v178
	v_lshlrev_b32_e32 v230, 16, v179
	v_and_b32_e32 v231, 0xffff0000, v179
	v_fma_f32 v40, v40, v228, v224
	v_fma_f32 v41, v41, v229, v225
	v_fma_f32 v42, v42, v230, v226
	v_fma_f32 v43, v43, v231, v227
	v_mul_f32_e32 v232, v41, v41
	v_mul_f32_e32 v233, v43, v43
	v_fmac_f32_e32 v232, v40, v40
	v_fmac_f32_e32 v233, v42, v42
	v_add_f32_e32 v235, v232, v233
	v_cvt_pk_bf16_f32 v44, v44, v45
	v_cvt_pk_bf16_f32 v45, v46, v47
	v_cvt_pk_bf16_f32 v46, v40, v41
	v_cvt_pk_bf16_f32 v47, v42, v43
	v_add_u32_e32 v250, 0x48000, v172
	global_store_dwordx4 v250, v[44:47], s[0:1]
	v_mul_f32_e32 v36, v36, v253
	v_mul_f32_e32 v37, v37, v253
	v_mul_f32_e32 v38, v38, v253
	v_mul_f32_e32 v39, v39, v253
	v_exp_f32_e32 v36, v36
	v_exp_f32_e32 v37, v37
	v_exp_f32_e32 v38, v38
	v_exp_f32_e32 v39, v39
	v_add_f32_e32 v36, 1.0, v36
	v_add_f32_e32 v37, 1.0, v37
	v_add_f32_e32 v38, 1.0, v38
	v_add_f32_e32 v39, 1.0, v39
	v_rcp_f32_e32 v36, v36
	v_rcp_f32_e32 v37, v37
	v_rcp_f32_e32 v38, v38
	v_rcp_f32_e32 v39, v39
	v_lshlrev_b32_e32 v224, 16, v168
	v_and_b32_e32 v225, 0xffff0000, v168
	v_lshlrev_b32_e32 v226, 16, v169
	v_and_b32_e32 v227, 0xffff0000, v169
	v_lshlrev_b32_e32 v228, 16, v180
	v_and_b32_e32 v229, 0xffff0000, v180
	v_lshlrev_b32_e32 v230, 16, v181
	v_and_b32_e32 v231, 0xffff0000, v181
	v_fma_f32 v36, v36, v228, v224
	v_fma_f32 v37, v37, v229, v225
	v_fma_f32 v38, v38, v230, v226
	v_fma_f32 v39, v39, v231, v227
	v_mul_f32_e32 v232, v37, v37
	v_mul_f32_e32 v233, v39, v39
	v_fmac_f32_e32 v232, v36, v36
	v_fmac_f32_e32 v233, v38, v38
	v_add_f32_e32 v248, v232, v233
	v_mul_f32_e32 v32, v32, v253
	v_mul_f32_e32 v33, v33, v253
	v_mul_f32_e32 v34, v34, v253
	v_mul_f32_e32 v35, v35, v253
; __device__ __forceinline__ u32x4 pack8(const f32x4 v0, const f32x4 v1) { u32x4 w; w.x = cvt_pk_bf16(v0[0], v0[1]); w.y = cvt_pk_bf16(v0[2], v0[3]); w.z = cvt_pk_bf16(v1[0], v1[1]); w.w = cvt_pk_bf16(v1[2], v1[3]); return w; }
; __device__ __forceinline__ float sumsq8(const f32x4 a, const f32x4 b) { return ((a[0] * a[0] + a[1] * a[1]) + (a[2] * a[2] + a[3] * a[3])) + ((b[0] * b[0] + b[1] * b[1]) + (b[2] * b[2] + b[3] * b[3])); }
; __device__ __forceinline__ void unpack8(const u32x4 w, f32x4& a, f32x4& b) { a = (f32x4){bf_lo(w.x), bf_hi(w.x), bf_lo(w.y), bf_hi(w.y)}; b = (f32x4){bf_lo(w.z), bf_hi(w.z), bf_lo(w.w), bf_hi(w.w)}; }
;     __device__ __forceinline__ void operator()(const f32x4 (&acc)[2][2][4][2], const Unit& u, int wr, int wc, int fr, int fq) const {
;     ...
;             for (int mm = 0; mm < 2; ++mm) { const int rowl = row0 + ai * HALF + (2 * mh + mm) * 16; p[mm] = *(const f32x4*)(ssq_in + (size_t)rowl * 16 + 4 * fq);
; #pragma unroll
;                 for (int bj = 0; bj < 2; ++bj) { const size_t off = (size_t)rowl * DMODEL + col0 + bj * HALF; rv[mm][bj] = *(const u32x4*)(Rin + off); pw[mm][bj] = *(const u32x4*)(PP + off); } }
; #pragma unroll
;             for (int mm = 0; mm < 2; ++mm) { const int m = 2 * mh + mm; const int row = row0 + ai * HALF + m * 16; float part = 0.f;
;                 float sr = (p[mm][0] + p[mm][1]) + (p[mm][2] + p[mm][3]); sr += __shfl_xor(sr, 16); sr += __shfl_xor(sr, 32); const float r = __builtin_amdgcn_rsqf(sr * (1.0f / DMODEL) + RMS_EPS);
; #pragma unroll
;                 for (int bj = 0; bj < 2; ++bj) { f32x4 r0, r1, p0, p1; unpack8(rv[mm][bj], r0, r1); unpack8(pw[mm][bj], p0, p1);
;                     f32x4 g0 = acc[ai][bj][m][0] * r, g1 = acc[ai][bj][m][1] * r;
; #pragma unroll
;                     for (int e = 0; e < 4; ++e) { g0[e] = __builtin_amdgcn_rcpf(1.f + __builtin_amdgcn_exp2f(-1.4426950408889634f * g0[e])); g1[e] = __builtin_amdgcn_rcpf(1.f + __builtin_amdgcn_exp2f(-1.4426950408889634f * g1[e])); }
;                     const f32x4 h0 = r0 + g0 * p0, h1 = r1 + g1 * p1; part += sumsq8(h0, h1);
;                     *(u32x4*)(XBo + (size_t)row * DMODEL + col0 + bj * HALF) = pack8(h0, h1); }
;                 part += __shfl_xor(part, 16); part += __shfl_xor(part, 32);
;                 if (fq == 0) ssq_out[(size_t)row * 16 + u.pn * 4 + wc] = part; }
	v_exp_f32_e32 v32, v32
	v_exp_f32_e32 v33, v33
	v_exp_f32_e32 v34, v34
	v_exp_f32_e32 v35, v35
	v_add_f32_e32 v32, 1.0, v32
	v_add_f32_e32 v33, 1.0, v33
	v_add_f32_e32 v34, 1.0, v34
	v_add_f32_e32 v35, 1.0, v35
	v_rcp_f32_e32 v32, v32
	v_rcp_f32_e32 v33, v33
	v_rcp_f32_e32 v34, v34
	v_rcp_f32_e32 v35, v35
	v_lshlrev_b32_e32 v224, 16, v170
	v_and_b32_e32 v225, 0xffff0000, v170
	v_lshlrev_b32_e32 v226, 16, v171
	v_and_b32_e32 v227, 0xffff0000, v171
	v_lshlrev_b32_e32 v228, 16, v182
	v_and_b32_e32 v229, 0xffff0000, v182
	v_lshlrev_b32_e32 v230, 16, v183
	v_and_b32_e32 v231, 0xffff0000, v183
	v_fma_f32 v32, v32, v228, v224
	v_fma_f32 v33, v33, v229, v225
	v_fma_f32 v34, v34, v230, v226
	v_fma_f32 v35, v35, v231, v227
	v_mul_f32_e32 v232, v33, v33
	v_mul_f32_e32 v233, v35, v35
	v_fmac_f32_e32 v232, v32, v32
	v_fmac_f32_e32 v233, v34, v34
	v_add_f32_e32 v249, v232, v233
	v_cvt_pk_bf16_f32 v36, v36, v37
	v_cvt_pk_bf16_f32 v37, v38, v39
	v_cvt_pk_bf16_f32 v38, v32, v33
	v_cvt_pk_bf16_f32 v39, v34, v35
	global_store_dwordx4 v250, v[36:39], s[0:1] offset:256
	v_add_f32_e32 v234, v234, v235
	v_add_f32_e32 v248, v248, v249
	v_add_f32_e32 v247, v234, v248
	v_mov_b32_e32 v252, v247
	s_nop 1
	v_permlane16_swap_b32_e32 v247, v252
	v_add_u32_e32 v251, 0x2400, v194
	v_add_f32_e32 v247, v247, v252
	v_mov_b32_e32 v252, v247
	s_nop 1
	v_permlane32_swap_b32_e32 v247, v252
	v_add_f32_e32 v247, v247, v252
	s_and_saveexec_b64 s[28:29], vcc
	global_store_dword v251, v247, s[12:13]
	s_or_b64 exec, exec, s[28:29]
	s_waitcnt vmcnt(17)
	v_add_f32_e32 v247, v108, v109
	v_add_f32_e32 v252, v110, v111
	v_add_f32_e32 v247, v247, v252
	v_mov_b32_e32 v252, v247
	s_nop 1
	v_permlane16_swap_b32_e32 v247, v252
	v_add_f32_e32 v247, v247, v252
	v_mov_b32_e32 v252, v247
	s_nop 1
	v_permlane32_swap_b32_e32 v247, v252
	v_add_f32_e32 v247, v247, v252
	v_fmamk_f32 v247, v247, 0x3a800000, v193
	v_rsq_f32_e32 v247, v247
	s_nop 0
	v_mul_f32_e32 v253, 0xbfb8aa3b, v247
	v_mul_f32_e32 v28, v28, v253
	v_mul_f32_e32 v29, v29, v253
	v_mul_f32_e32 v30, v30, v253
	v_mul_f32_e32 v31, v31, v253
	v_exp_f32_e32 v28, v28
	v_exp_f32_e32 v29, v29
	v_exp_f32_e32 v30, v30
	v_exp_f32_e32 v31, v31
	v_add_f32_e32 v28, 1.0, v28
	v_add_f32_e32 v29, 1.0, v29
	v_add_f32_e32 v30, 1.0, v30
	v_add_f32_e32 v31, 1.0, v31
	v_rcp_f32_e32 v28, v28
	v_rcp_f32_e32 v29, v29
	v_rcp_f32_e32 v30, v30
	v_rcp_f32_e32 v31, v31
	v_lshlrev_b32_e32 v224, 16, v104
	v_and_b32_e32 v225, 0xffff0000, v104
	v_lshlrev_b32_e32 v226, 16, v105
	v_and_b32_e32 v227, 0xffff0000, v105
	v_lshlrev_b32_e32 v228, 16, v96
	v_and_b32_e32 v229, 0xffff0000, v96
	v_lshlrev_b32_e32 v230, 16, v97
	v_and_b32_e32 v231, 0xffff0000, v97
	v_fma_f32 v28, v28, v228, v224
	v_fma_f32 v29, v29, v229, v225
	v_fma_f32 v30, v30, v230, v226
	v_fma_f32 v31, v31, v231, v227
	v_mul_f32_e32 v232, v29, v29
	v_mul_f32_e32 v233, v31, v31
	v_fmac_f32_e32 v232, v28, v28
	v_fmac_f32_e32 v233, v30, v30
	v_add_f32_e32 v234, v232, v233
	v_mul_f32_e32 v24, v24, v253
	v_mul_f32_e32 v25, v25, v253
	v_mul_f32_e32 v26, v26, v253
	v_mul_f32_e32 v27, v27, v253
	v_exp_f32_e32 v24, v24
	v_exp_f32_e32 v25, v25
	v_exp_f32_e32 v26, v26
	v_exp_f32_e32 v27, v27
	v_add_f32_e32 v24, 1.0, v24
	v_add_f32_e32 v25, 1.0, v25
	v_add_f32_e32 v26, 1.0, v26
	v_add_f32_e32 v27, 1.0, v27
	v_rcp_f32_e32 v24, v24
	v_rcp_f32_e32 v25, v25
	v_rcp_f32_e32 v26, v26
	v_rcp_f32_e32 v27, v27
	v_lshlrev_b32_e32 v224, 16, v106
	v_and_b32_e32 v225, 0xffff0000, v106
	v_lshlrev_b32_e32 v226, 16, v107
	v_and_b32_e32 v227, 0xffff0000, v107
	v_lshlrev_b32_e32 v228, 16, v98
	v_and_b32_e32 v229, 0xffff0000, v98
	v_lshlrev_b32_e32 v230, 16, v99
	v_and_b32_e32 v231, 0xffff0000, v99
	v_fma_f32 v24, v24, v228, v224
	v_fma_f32 v25, v25, v229, v225
	v_fma_f32 v26, v26, v230, v226
	v_fma_f32 v27, v27, v231, v227
	v_mul_f32_e32 v232, v25, v25
	v_mul_f32_e32 v233, v27, v27
	v_fmac_f32_e32 v232, v24, v24
	v_fmac_f32_e32 v233, v26, v26
	v_add_f32_e32 v235, v232, v233
	v_cvt_pk_bf16_f32 v28, v28, v29
	v_cvt_pk_bf16_f32 v29, v30, v31
	v_cvt_pk_bf16_f32 v30, v24, v25
	v_cvt_pk_bf16_f32 v31, v26, v27
	v_add_u32_e32 v250, 0x50000, v172
	global_store_dwordx4 v250, v[28:31], s[0:1]
	v_mul_f32_e32 v20, v20, v253
	v_mul_f32_e32 v21, v21, v253
	v_mul_f32_e32 v22, v22, v253
	v_mul_f32_e32 v23, v23, v253
	v_exp_f32_e32 v20, v20
	v_exp_f32_e32 v21, v21
	v_exp_f32_e32 v22, v22
	v_exp_f32_e32 v23, v23
	v_add_f32_e32 v20, 1.0, v20
	v_add_f32_e32 v21, 1.0, v21
	v_add_f32_e32 v22, 1.0, v22
	v_add_f32_e32 v23, 1.0, v23
	v_rcp_f32_e32 v20, v20
	v_rcp_f32_e32 v21, v21
	v_rcp_f32_e32 v22, v22
	v_rcp_f32_e32 v23, v23
	v_lshlrev_b32_e32 v224, 16, v100
	v_and_b32_e32 v225, 0xffff0000, v100
	v_lshlrev_b32_e32 v226, 16, v101
	v_and_b32_e32 v227, 0xffff0000, v101
	v_lshlrev_b32_e32 v228, 16, v220
	v_and_b32_e32 v229, 0xffff0000, v220
	v_lshlrev_b32_e32 v230, 16, v221
	v_and_b32_e32 v231, 0xffff0000, v221
	v_fma_f32 v20, v20, v228, v224
	v_fma_f32 v21, v21, v229, v225
	v_fma_f32 v22, v22, v230, v226
	v_fma_f32 v23, v23, v231, v227
	v_mul_f32_e32 v232, v21, v21
	v_mul_f32_e32 v233, v23, v23
	v_fmac_f32_e32 v232, v20, v20
	v_fmac_f32_e32 v233, v22, v22
	v_add_f32_e32 v248, v232, v233
	v_mul_f32_e32 v16, v16, v253
	v_mul_f32_e32 v17, v17, v253
	v_mul_f32_e32 v18, v18, v253
	v_mul_f32_e32 v19, v19, v253
	v_exp_f32_e32 v16, v16
	v_exp_f32_e32 v17, v17
	v_exp_f32_e32 v18, v18
	v_exp_f32_e32 v19, v19
	v_add_f32_e32 v16, 1.0, v16
	v_add_f32_e32 v17, 1.0, v17
	v_add_f32_e32 v18, 1.0, v18
	v_add_f32_e32 v19, 1.0, v19
	v_rcp_f32_e32 v16, v16
	v_rcp_f32_e32 v17, v17
	v_rcp_f32_e32 v18, v18
	v_rcp_f32_e32 v19, v19
	v_lshlrev_b32_e32 v224, 16, v102
	v_and_b32_e32 v225, 0xffff0000, v102
	v_lshlrev_b32_e32 v226, 16, v103
	v_and_b32_e32 v227, 0xffff0000, v103
	v_lshlrev_b32_e32 v228, 16, v222
	v_and_b32_e32 v229, 0xffff0000, v222
	v_lshlrev_b32_e32 v230, 16, v223
	v_and_b32_e32 v231, 0xffff0000, v223
	v_fma_f32 v16, v16, v228, v224
	v_fma_f32 v17, v17, v229, v225
	v_fma_f32 v18, v18, v230, v226
	v_fma_f32 v19, v19, v231, v227
	v_mul_f32_e32 v232, v17, v17
	v_mul_f32_e32 v233, v19, v19
	v_fmac_f32_e32 v232, v16, v16
	v_fmac_f32_e32 v233, v18, v18
	v_add_f32_e32 v249, v232, v233
	v_cvt_pk_bf16_f32 v20, v20, v21
	v_cvt_pk_bf16_f32 v21, v22, v23
	v_cvt_pk_bf16_f32 v22, v16, v17
	v_cvt_pk_bf16_f32 v23, v18, v19
	global_store_dwordx4 v250, v[20:23], s[0:1] offset:256
	v_add_f32_e32 v234, v234, v235
	v_add_f32_e32 v248, v248, v249
	v_add_f32_e32 v247, v234, v248
	v_mov_b32_e32 v252, v247
	s_nop 1
	v_permlane16_swap_b32_e32 v247, v252
	v_add_u32_e32 v251, 0x2800, v194
	v_add_f32_e32 v247, v247, v252
	v_mov_b32_e32 v252, v247
	s_nop 1
	v_permlane32_swap_b32_e32 v247, v252
	v_add_f32_e32 v247, v247, v252
	s_and_saveexec_b64 s[28:29], vcc
	global_store_dword v251, v247, s[12:13]
	s_or_b64 exec, exec, s[28:29]
	s_waitcnt vmcnt(12)
;     __device__ __forceinline__ void operator()(const f32x4 (&acc)[2][2][4][2], const Unit& u, int wr, int wc, int fr, int fq) const {
;     ...
;             for (int mm = 0; mm < 2; ++mm) { const int rowl = row0 + ai * HALF + (2 * mh + mm) * 16; p[mm] = *(const f32x4*)(ssq_in + (size_t)rowl * 16 + 4 * fq);
; #pragma unroll
;                 for (int bj = 0; bj < 2; ++bj) { const size_t off = (size_t)rowl * DMODEL + col0 + bj * HALF; rv[mm][bj] = *(const u32x4*)(Rin + off); pw[mm][bj] = *(const u32x4*)(PP + off); } }
; #pragma unroll
;             for (int mm = 0; mm < 2; ++mm) { const int m = 2 * mh + mm; const int row = row0 + ai * HALF + m * 16; float part = 0.f;
;                 float sr = (p[mm][0] + p[mm][1]) + (p[mm][2] + p[mm][3]); sr += __shfl_xor(sr, 16); sr += __shfl_xor(sr, 32); const float r = __builtin_amdgcn_rsqf(sr * (1.0f / DMODEL) + RMS_EPS);
; #pragma unroll
;                 for (int bj = 0; bj < 2; ++bj) { f32x4 r0, r1, p0, p1; unpack8(rv[mm][bj], r0, r1); unpack8(pw[mm][bj], p0, p1);
;                     f32x4 g0 = acc[ai][bj][m][0] * r, g1 = acc[ai][bj][m][1] * r;
; #pragma unroll
;                     for (int e = 0; e < 4; ++e) { g0[e] = __builtin_amdgcn_rcpf(1.f + __builtin_amdgcn_exp2f(-1.4426950408889634f * g0[e])); g1[e] = __builtin_amdgcn_rcpf(1.f + __builtin_amdgcn_exp2f(-1.4426950408889634f * g1[e])); }
;                     const f32x4 h0 = r0 + g0 * p0, h1 = r1 + g1 * p1; part += sumsq8(h0, h1);
;                     *(u32x4*)(XBo + (size_t)row * DMODEL + col0 + bj * HALF) = pack8(h0, h1); }
;                 part += __shfl_xor(part, 16); part += __shfl_xor(part, 32);
;                 if (fq == 0) ssq_out[(size_t)row * 16 + u.pn * 4 + wc] = part; }
; template <class Epi, class Sched, bool ALIGN_EPI = false, bool SP2 = false>
; __device__ __forceinline__ void gemm_phase(PG8_LAS unsigned char* lds, const Gemm g, const Sched& S, const Epi& E) {
;     ...
;         if (!has_next) break;
; #pragma unroll
;         for (int a = 0; a < 2; ++a)
; #pragma unroll
;             for (int b = 0; b < 2; ++b)
; #pragma unroll
;                 for (int m = 0; m < 4; ++m)
; #pragma unroll
;                     for (int n = 0; n < 2; ++n) acc[a][b][m][n] = (f32x4){0.f, 0.f, 0.f, 0.f};
;         cur = nxt; cA = nA; cB = nB; ++ui; relax = Epi::LOADS_BEFORE_STORES && !Epi::AFTER_DRAIN && SP2;
;         if constexpr (ALIGN_EPI) { if (wr == 1) PG8_BAR; }
	v_add_f32_e32 v247, v184, v185
	v_add_f32_e32 v252, v186, v187
	v_add_f32_e32 v247, v247, v252
	v_mov_b32_e32 v252, v247
	s_nop 1
	v_permlane16_swap_b32_e32 v247, v252
	v_add_f32_e32 v247, v247, v252
	v_mov_b32_e32 v252, v247
	s_nop 1
	v_permlane32_swap_b32_e32 v247, v252
	v_add_f32_e32 v247, v247, v252
	v_fmamk_f32 v247, v247, 0x3a800000, v193
	v_rsq_f32_e32 v247, v247
	s_nop 0
	v_mul_f32_e32 v253, 0xbfb8aa3b, v247
	v_mul_f32_e32 v12, v12, v253
	v_mul_f32_e32 v13, v13, v253
	v_mul_f32_e32 v14, v14, v253
	v_mul_f32_e32 v15, v15, v253
	v_exp_f32_e32 v12, v12
	v_exp_f32_e32 v13, v13
	v_exp_f32_e32 v14, v14
	v_exp_f32_e32 v15, v15
	v_add_f32_e32 v12, 1.0, v12
	v_add_f32_e32 v13, 1.0, v13
	v_add_f32_e32 v14, 1.0, v14
	v_add_f32_e32 v15, 1.0, v15
	v_rcp_f32_e32 v12, v12
	v_rcp_f32_e32 v13, v13
	v_rcp_f32_e32 v14, v14
	v_rcp_f32_e32 v15, v15
	v_lshlrev_b32_e32 v224, 16, v188
	v_and_b32_e32 v225, 0xffff0000, v188
	v_lshlrev_b32_e32 v226, 16, v189
	v_and_b32_e32 v227, 0xffff0000, v189
	v_lshlrev_b32_e32 v228, 16, v208
	v_and_b32_e32 v229, 0xffff0000, v208
	v_lshlrev_b32_e32 v230, 16, v209
	v_and_b32_e32 v231, 0xffff0000, v209
	v_fma_f32 v12, v12, v228, v224
	v_fma_f32 v13, v13, v229, v225
	v_fma_f32 v14, v14, v230, v226
	v_fma_f32 v15, v15, v231, v227
	v_mul_f32_e32 v232, v13, v13
	v_mul_f32_e32 v233, v15, v15
	v_fmac_f32_e32 v232, v12, v12
	v_fmac_f32_e32 v233, v14, v14
	v_add_f32_e32 v234, v232, v233
	v_mul_f32_e32 v8, v8, v253
	v_mul_f32_e32 v9, v9, v253
	v_mul_f32_e32 v10, v10, v253
	v_mul_f32_e32 v11, v11, v253
	v_exp_f32_e32 v8, v8
	v_exp_f32_e32 v9, v9
	v_exp_f32_e32 v10, v10
	v_exp_f32_e32 v11, v11
	v_add_f32_e32 v8, 1.0, v8
	v_add_f32_e32 v9, 1.0, v9
	v_add_f32_e32 v10, 1.0, v10
	v_add_f32_e32 v11, 1.0, v11
	v_rcp_f32_e32 v8, v8
	v_rcp_f32_e32 v9, v9
	v_rcp_f32_e32 v10, v10
	v_rcp_f32_e32 v11, v11
	v_lshlrev_b32_e32 v224, 16, v190
	v_and_b32_e32 v225, 0xffff0000, v190
	v_lshlrev_b32_e32 v226, 16, v191
	v_and_b32_e32 v227, 0xffff0000, v191
	v_lshlrev_b32_e32 v228, 16, v210
	v_and_b32_e32 v229, 0xffff0000, v210
	v_lshlrev_b32_e32 v230, 16, v211
	v_and_b32_e32 v231, 0xffff0000, v211
	v_fma_f32 v8, v8, v228, v224
	v_fma_f32 v9, v9, v229, v225
	v_fma_f32 v10, v10, v230, v226
	v_fma_f32 v11, v11, v231, v227
	v_mul_f32_e32 v232, v9, v9
	v_mul_f32_e32 v233, v11, v11
	v_fmac_f32_e32 v232, v8, v8
	v_fmac_f32_e32 v233, v10, v10
	v_add_f32_e32 v235, v232, v233
	v_cvt_pk_bf16_f32 v12, v12, v13
	v_cvt_pk_bf16_f32 v13, v14, v15
	v_cvt_pk_bf16_f32 v14, v8, v9
	v_cvt_pk_bf16_f32 v15, v10, v11
	v_add_u32_e32 v250, 0x58000, v172
	global_store_dwordx4 v250, v[12:15], s[0:1]
	v_mul_f32_e32 v4, v4, v253
	v_mul_f32_e32 v5, v5, v253
	v_mul_f32_e32 v6, v6, v253
	v_mul_f32_e32 v7, v7, v253
	v_exp_f32_e32 v4, v4
	v_exp_f32_e32 v5, v5
	v_exp_f32_e32 v6, v6
	v_exp_f32_e32 v7, v7
	v_add_f32_e32 v4, 1.0, v4
	v_add_f32_e32 v5, 1.0, v5
	v_add_f32_e32 v6, 1.0, v6
	v_add_f32_e32 v7, 1.0, v7
	v_rcp_f32_e32 v4, v4
	v_rcp_f32_e32 v5, v5
	v_rcp_f32_e32 v6, v6
	v_rcp_f32_e32 v7, v7
	v_lshlrev_b32_e32 v224, 16, v204
	v_and_b32_e32 v225, 0xffff0000, v204
	v_lshlrev_b32_e32 v226, 16, v205
	v_and_b32_e32 v227, 0xffff0000, v205
	v_lshlrev_b32_e32 v228, 16, v212
	v_and_b32_e32 v229, 0xffff0000, v212
	v_lshlrev_b32_e32 v230, 16, v213
	v_and_b32_e32 v231, 0xffff0000, v213
	v_fma_f32 v4, v4, v228, v224
	v_fma_f32 v5, v5, v229, v225
	v_fma_f32 v6, v6, v230, v226
	v_fma_f32 v7, v7, v231, v227
	v_mul_f32_e32 v232, v5, v5
	v_mul_f32_e32 v233, v7, v7
	v_fmac_f32_e32 v232, v4, v4
	v_fmac_f32_e32 v233, v6, v6
	v_add_f32_e32 v248, v232, v233
	v_mul_f32_e32 v0, v0, v253
	v_mul_f32_e32 v1, v1, v253
	v_mul_f32_e32 v2, v2, v253
	v_mul_f32_e32 v3, v3, v253
	v_exp_f32_e32 v0, v0
	v_exp_f32_e32 v1, v1
	v_exp_f32_e32 v2, v2
	v_exp_f32_e32 v3, v3
	v_add_f32_e32 v0, 1.0, v0
	v_add_f32_e32 v1, 1.0, v1
	v_add_f32_e32 v2, 1.0, v2
	v_add_f32_e32 v3, 1.0, v3
	v_rcp_f32_e32 v0, v0
	v_rcp_f32_e32 v1, v1
	v_rcp_f32_e32 v2, v2
	v_rcp_f32_e32 v3, v3
	v_lshlrev_b32_e32 v224, 16, v206
	v_and_b32_e32 v225, 0xffff0000, v206
	v_lshlrev_b32_e32 v226, 16, v207
	v_and_b32_e32 v227, 0xffff0000, v207
	v_lshlrev_b32_e32 v228, 16, v214
	v_and_b32_e32 v229, 0xffff0000, v214
	v_lshlrev_b32_e32 v230, 16, v215
	v_and_b32_e32 v231, 0xffff0000, v215
	v_fma_f32 v0, v0, v228, v224
	v_fma_f32 v1, v1, v229, v225
	v_fma_f32 v2, v2, v230, v226
	v_fma_f32 v3, v3, v231, v227
	v_mul_f32_e32 v232, v1, v1
	v_mul_f32_e32 v233, v3, v3
	v_fmac_f32_e32 v232, v0, v0
	v_fmac_f32_e32 v233, v2, v2
	v_add_f32_e32 v249, v232, v233
	v_cvt_pk_bf16_f32 v4, v4, v5
	v_cvt_pk_bf16_f32 v5, v6, v7
	v_cvt_pk_bf16_f32 v6, v0, v1
	v_cvt_pk_bf16_f32 v7, v2, v3
	global_store_dwordx4 v250, v[4:7], s[0:1] offset:256
	v_add_f32_e32 v234, v234, v235
	v_add_f32_e32 v248, v248, v249
	v_add_f32_e32 v247, v234, v248
	v_mov_b32_e32 v252, v247
	s_nop 1
	v_permlane16_swap_b32_e32 v247, v252
	v_add_u32_e32 v251, 0x2c00, v194
	v_add_f32_e32 v247, v247, v252
	v_mov_b32_e32 v252, v247
	s_nop 1
	v_permlane32_swap_b32_e32 v247, v252
	v_add_f32_e32 v247, v247, v252
	s_and_saveexec_b64 s[28:29], vcc
	global_store_dword v251, v247, s[12:13]
	s_or_b64 exec, exec, s[28:29]
	s_mov_b64 s[62:63], -1
	s_andn2_b64 vcc, exec, s[20:21]
	s_mov_b64 s[20:21], -1
	s_cbranch_vccnz .LBB0_1123
	s_andn2_b64 vcc, exec, s[8:9]
	s_cbranch_vccnz .LBB0_1122
	s_barrier
	s_branch .LBB0_1122
